# out phase: K loop fully unrolled, the f32 x tile of the epilogue is fetched one 16-byte load per K step (counted vmcnt keeps it in flight a step longer); epilogue only loads the gate vector
# speedup vs baseline: 1.1302x; 1.0020x over previous
; DEV int bid_() { int b = blockIdx.x; asm volatile("" : "+s"(b)); return b; }
; __device__ void phase_out(PRef p, int l, const bf16* M, const float* xl, const float* xc, bf16* sA, bf16* sB) {
;     ...
;   for (int t = bid_() >> 3; t < 36 * 8; t += per_) {
;     int rt = xcd_ + 8 * (t / 8), ct = t % 8;
;     if (skip_rt(l, rt)) continue;
;     f32x16 acc[2][2];
;     zero_acc<2>(acc);
;     gemm_tile<2>(acc, M + (size_t)rt * 128 * 1024, 1024, p.WOUT + (size_t)ct * 128 * 1024, 1024, 1024, sA, sB);
;     int b = rt / 18;
;     bool isctx = (rt % 18) < 2;
;     const float* gate = p.MOD + ((size_t)l * 17 + (isctx ? 16 : b)) * 3072 + 2048;
;     stage_tile<2>(acc, sA);
;     TILE_CHUNKS(2, sA, {
;       int R = rt * 128 + trow;
;       int col = ct * 128 + tcol;
;       int tp = R % TPB;
;       const float* xin;
;       float* dstp;
;       if (isctx) {
;         xin = xc + ((size_t)b * 256 + tp) * 1024 + col;
;         dstp = p.XC + ((size_t)b * 256 + tp) * 1024 + col;
;       } else {
;         xin = xl + ((size_t)b * 2048 + (tp - 256)) * 1024 + col;
;         dstp = p.out + ((size_t)b * 2048 + (tp - 256)) * 1024 + col;
.LBB0_1082:
	s_ashr_i32 s4, s28, 31
	s_lshr_b32 s4, s4, 29
	s_add_i32 s5, s28, s4
	s_and_b32 s4, s5, -8
	s_or_b32 s4, s4, s34
	s_mul_hi_i32 s14, s4, 0x38e38e39
	s_lshr_b32 s15, s14, 31
	s_ashr_i32 s14, s14, 2
	s_add_i32 s18, s14, s15
	s_mul_i32 s14, s18, 18
	s_sub_i32 s14, s4, s14
	s_cmp_lt_i32 s14, 2
	s_cselect_b64 s[22:23], -1, 0
	s_cmp_gt_i32 s14, 1
	s_cselect_b64 s[24:25], -1, 0
	s_and_b64 s[14:15], s[6:7], s[22:23]
	s_and_b64 vcc, exec, s[14:15]
	s_cbranch_vccnz .LBB0_1081
	s_ashr_i32 s5, s5, 3
	s_lshl_b32 s5, s5, 3
	s_sub_i32 s20, s28, s5
	s_lshl_b32 s14, s4, 18
	s_add_u32 s98, s70, s14
	s_addc_u32 s99, s71, 0
	s_lshl_b32 s14, s20, 18
	s_waitcnt lgkmcnt(0)
	s_add_u32 s100, s12, s14
	s_addc_u32 s101, s13, 0
	s_lshl_b32 s36, s4, 7
	s_mul_i32 s14, s18, 0x900
	s_sub_u32 s14, s36, s14
	s_andn2_b64 vcc, exec, s[24:25]
	s_cbranch_vccnz .Lout_ctx
	s_sub_u32 s14, s14, 0x100
	s_lshl_b32 s15, s18, 11
	s_mov_b64 s[30:31], s[40:41]
	s_mov_b64 s[26:27], s[10:11]
	s_branch .Lout_ptr

; DEV int tid_() { int t = threadIdx.x; asm volatile("" : "+v"(t)); return t; }
; template <int NI, bool DEEP = true>
; DEV void gemm_tile(f32x16 (&acc)[2][NI], const bf16* __restrict__ A, int lda, const bf16* __restrict__ Bt, int ldb,
;                    int K, bf16* sA, bf16* sB) {
;   int tid = tid_(), lane = tid & 63, wave = tid >> 6;
;   int wm = wave >> 1, wn = wave & 1;
;   int lr = tid >> 3, lc = (tid & 7) * 8;
;   const bf16* Ap = A + (size_t)lr * lda + lc;
;   const bf16* Bp = Bt + (size_t)lr * ldb + lc;
;   u32x4 ra0[4], rb0[2 * NI], ra1[4], rb1[2 * NI];
;     ...
;   G_LOAD(ra0, rb0, 0)
;   if (DEEP) {
;     if (64 < K) G_LOAD(ra1, rb1, 64)
;     for (int k0 = 0; k0 < K; k0 += 128) {
;       G_STEP(ra0, rb0, k0 + 128)
;       if (k0 + 64 < K) G_STEP(ra1, rb1, k0 + 192)
;     }
; __device__ void phase_out(PRef p, int l, const bf16* M, const float* xl, const float* xc, bf16* sA, bf16* sB) {
;     ...
;       int R = rt * 128 + trow;
;       int col = ct * 128 + tcol;
;       int tp = R % TPB;
;       const float* xin;
;       float* dstp;
;       if (isctx) {
;         xin = xc + ((size_t)b * 256 + tp) * 1024 + col;
;         dstp = p.XC + ((size_t)b * 256 + tp) * 1024 + col;
;       } else {
;         xin = xl + ((size_t)b * 2048 + (tp - 256)) * 1024 + col;
;         dstp = p.out + ((size_t)b * 2048 + (tp - 256)) * 1024 + col;
;       }
;       f32x4v x0 = *(const f32x4v*)xin, x1 = *(const f32x4v*)(xin + 4);
.Lout_ptr:
	s_add_u32 s14, s14, s15
	s_lshl_b32 s16, s14, 12
	s_lshl_b32 s14, s20, 9
	s_add_u32 s16, s16, s14
	s_add_u32 s30, s30, s16
	s_addc_u32 s31, s31, 0
	s_add_u32 s26, s26, s16
	s_addc_u32 s27, s27, 0
	v_lshrrev_b32_e32 v242, 4, v196
	v_and_b32_e32 v243, 15, v196
	v_lshlrev_b32_e32 v242, 12, v242
	v_lshl_add_u32 v242, v243, 5, v242
	v_and_b32_e32 v0, 63, v196
	v_lshrrev_b32_e32 v1, 6, v196
	v_lshrrev_b32_e32 v2, 3, v0
	v_readfirstlane_b32 s16, v1
	v_lshrrev_b32_e32 v78, 1, v2
	v_and_b32_e32 v79, 7, v0
	v_xor_b32_e32 v78, v79, v78
	v_lshlrev_b32_e32 v78, 4, v78
	v_lshl_or_b32 v68, v2, 11, v78
	v_xor_b32_e32 v69, 64, v68
	v_lshrrev_b32_e32 v78, 5, v0
	v_bfe_u32 v79, v0, 1, 3
	v_and_b32_e32 v2, 31, v0
	v_lshrrev_b32_e32 v0, 1, v1
	v_and_b32_e32 v1, 1, v1
	v_lshl_add_u32 v0, v0, 6, v2
	v_lshl_add_u32 v1, v1, 6, v2
	v_lshlrev_b32_e32 v0, 7, v0
	v_lshlrev_b32_e32 v1, 7, v1
	v_add_u32_e32 v1, 0x4000, v1
	v_add_u32_e32 v2, 0, v78
	v_xor_b32_e32 v2, v2, v79
	v_lshl_add_u32 v70, v2, 4, v0
	v_lshl_add_u32 v74, v2, 4, v1
	v_add_u32_e32 v2, 2, v78
	v_xor_b32_e32 v2, v2, v79
	v_lshl_add_u32 v71, v2, 4, v0
	v_lshl_add_u32 v75, v2, 4, v1
	v_add_u32_e32 v2, 4, v78
	v_xor_b32_e32 v2, v2, v79
	v_lshl_add_u32 v72, v2, 4, v0
	v_lshl_add_u32 v76, v2, 4, v1
	v_add_u32_e32 v2, 6, v78
	v_xor_b32_e32 v2, v2, v79
	v_lshl_add_u32 v73, v2, 4, v0
	v_lshl_add_u32 v77, v2, 4, v1
	s_lshl_b32 s17, s16, 16
	s_lshl_b32 s16, s16, 12
	s_add_u32 s98, s98, s17
	s_addc_u32 s99, s99, 0
	s_add_u32 s100, s100, s17
	s_addc_u32 s101, s101, 0
	s_waitcnt lgkmcnt(0)
	s_barrier
	s_add_u32 m0, s16, 0x0
	s_nop 0
	global_load_lds_dwordx4 v68, s[98:99]
	s_add_u32 m0, s16, 0x400
	s_add_u32 s14, s98, 0x4000
	s_addc_u32 s15, s99, 0
	global_load_lds_dwordx4 v69, s[14:15]
	s_add_u32 m0, s16, 0x800
	s_add_u32 s14, s98, 0x8000
	s_addc_u32 s15, s99, 0
	global_load_lds_dwordx4 v68, s[14:15]
	s_add_u32 m0, s16, 0xc00
	s_add_u32 s14, s98, 0xc000
	s_addc_u32 s15, s99, 0
	global_load_lds_dwordx4 v69, s[14:15]
	s_add_u32 m0, s16, 0x4000
	s_nop 0
	global_load_lds_dwordx4 v68, s[100:101]
	s_add_u32 m0, s16, 0x4400
	s_add_u32 s14, s100, 0x4000
	s_addc_u32 s15, s101, 0
	global_load_lds_dwordx4 v69, s[14:15]
	s_add_u32 m0, s16, 0x4800
	s_add_u32 s14, s100, 0x8000
	s_addc_u32 s15, s101, 0
	global_load_lds_dwordx4 v68, s[14:15]
	s_add_u32 m0, s16, 0x4c00
	s_add_u32 s14, s100, 0xc000
	s_addc_u32 s15, s101, 0
	global_load_lds_dwordx4 v69, s[14:15]
	s_add_u32 s98, s98, 0x80
	s_addc_u32 s99, s99, 0
	s_add_u32 s100, s100, 0x80
	s_addc_u32 s101, s101, 0
	v_mov_b32_e32 v4, 0
	v_mov_b32_e32 v5, 0
	v_mov_b32_e32 v6, 0
	v_mov_b32_e32 v7, 0
	v_mov_b32_e32 v8, 0
	v_mov_b32_e32 v9, 0
	v_mov_b32_e32 v10, 0
	v_mov_b32_e32 v11, 0
	v_mov_b32_e32 v12, 0
	v_mov_b32_e32 v13, 0
	v_mov_b32_e32 v14, 0
	v_mov_b32_e32 v15, 0
	v_mov_b32_e32 v16, 0
	v_mov_b32_e32 v17, 0
	v_mov_b32_e32 v18, 0
	v_mov_b32_e32 v19, 0
	v_mov_b32_e32 v20, 0
	v_mov_b32_e32 v21, 0
	v_mov_b32_e32 v22, 0
	v_mov_b32_e32 v23, 0
	v_mov_b32_e32 v24, 0
	v_mov_b32_e32 v25, 0
	v_mov_b32_e32 v26, 0
	v_mov_b32_e32 v27, 0
	v_mov_b32_e32 v28, 0
	v_mov_b32_e32 v29, 0
	v_mov_b32_e32 v30, 0
	v_mov_b32_e32 v31, 0
	v_mov_b32_e32 v32, 0
	v_mov_b32_e32 v33, 0
	v_mov_b32_e32 v34, 0
	v_mov_b32_e32 v35, 0
	v_mov_b32_e32 v36, 0
	v_mov_b32_e32 v37, 0
	v_mov_b32_e32 v38, 0
	v_mov_b32_e32 v39, 0
	v_mov_b32_e32 v40, 0
	v_mov_b32_e32 v41, 0
	v_mov_b32_e32 v42, 0
	v_mov_b32_e32 v43, 0
	v_mov_b32_e32 v44, 0
	v_mov_b32_e32 v45, 0
	v_mov_b32_e32 v46, 0
	v_mov_b32_e32 v47, 0
	v_mov_b32_e32 v48, 0
	v_mov_b32_e32 v49, 0
	v_mov_b32_e32 v50, 0
	v_mov_b32_e32 v51, 0
	v_mov_b32_e32 v52, 0
	v_mov_b32_e32 v53, 0
	v_mov_b32_e32 v54, 0
	v_mov_b32_e32 v55, 0
	v_mov_b32_e32 v56, 0
	v_mov_b32_e32 v57, 0
	v_mov_b32_e32 v58, 0
	v_mov_b32_e32 v59, 0
	v_mov_b32_e32 v60, 0
	v_mov_b32_e32 v61, 0
	v_mov_b32_e32 v62, 0
	v_mov_b32_e32 v63, 0
	v_mov_b32_e32 v64, 0
	v_mov_b32_e32 v65, 0
	v_mov_b32_e32 v66, 0
	v_mov_b32_e32 v67, 0
	s_waitcnt vmcnt(0)
	s_barrier
	ds_read_b128 v[88:91], v74 offset:0
	ds_read_b128 v[80:83], v70 offset:0
	ds_read_b128 v[84:87], v70 offset:4096
	ds_read_b128 v[92:95], v74 offset:4096
	s_waitcnt lgkmcnt(2)
	v_mfma_f32_32x32x16_bf16 v[52:67], v[88:91], v[80:83], v[52:67]
	s_add_u32 m0, s16, 0x8000
	s_nop 0
	global_load_lds_dwordx4 v68, s[98:99]
	ds_read_b128 v[104:107], v75 offset:0
	ds_read_b128 v[96:99], v71 offset:0
	s_waitcnt lgkmcnt(3)
	v_mfma_f32_32x32x16_bf16 v[20:35], v[88:91], v[84:87], v[20:35]
	s_add_u32 m0, s16, 0x8400
	s_add_u32 s14, s98, 0x4000
	s_addc_u32 s15, s99, 0
	global_load_lds_dwordx4 v69, s[14:15]
	ds_read_b128 v[100:103], v71 offset:4096
	s_waitcnt lgkmcnt(3)
	v_mfma_f32_32x32x16_bf16 v[36:51], v[92:95], v[80:83], v[36:51]
	s_add_u32 m0, s16, 0x8800
	s_add_u32 s14, s98, 0x8000
	s_addc_u32 s15, s99, 0
	global_load_lds_dwordx4 v68, s[14:15]
	ds_read_b128 v[108:111], v75 offset:4096
	v_mfma_f32_32x32x16_bf16 v[4:19], v[92:95], v[84:87], v[4:19]
	s_add_u32 m0, s16, 0x8c00
	s_add_u32 s14, s98, 0xc000
	s_addc_u32 s15, s99, 0
	global_load_lds_dwordx4 v69, s[14:15]
	s_waitcnt lgkmcnt(2)
	v_mfma_f32_32x32x16_bf16 v[52:67], v[104:107], v[96:99], v[52:67]
	s_add_u32 m0, s16, 0xd840
	s_nop 0
	global_load_lds_dwordx4 v68, s[100:101]
	ds_read_b128 v[88:91], v76 offset:0
	ds_read_b128 v[80:83], v72 offset:0
	s_waitcnt lgkmcnt(3)
	v_mfma_f32_32x32x16_bf16 v[20:35], v[104:107], v[100:103], v[20:35]
	s_add_u32 m0, s16, 0xdc40
	s_add_u32 s14, s100, 0x4000
	s_addc_u32 s15, s101, 0
	global_load_lds_dwordx4 v69, s[14:15]
	ds_read_b128 v[84:87], v72 offset:4096
	s_waitcnt lgkmcnt(3)
	v_mfma_f32_32x32x16_bf16 v[36:51], v[108:111], v[96:99], v[36:51]
	s_add_u32 m0, s16, 0xe040
	s_add_u32 s14, s100, 0x8000
	s_addc_u32 s15, s101, 0
	global_load_lds_dwordx4 v68, s[14:15]
	ds_read_b128 v[92:95], v76 offset:4096
	v_mfma_f32_32x32x16_bf16 v[4:19], v[108:111], v[100:103], v[4:19]
	s_add_u32 m0, s16, 0xe440
	s_add_u32 s14, s100, 0xc000
	s_addc_u32 s15, s101, 0
	global_load_lds_dwordx4 v69, s[14:15]
	s_waitcnt lgkmcnt(2)
	v_mfma_f32_32x32x16_bf16 v[52:67], v[88:91], v[80:83], v[52:67]
	s_add_u32 s98, s98, 0x80
	s_addc_u32 s99, s99, 0
	s_add_u32 s100, s100, 0x80
	s_addc_u32 s101, s101, 0
	ds_read_b128 v[104:107], v77 offset:0
	ds_read_b128 v[96:99], v73 offset:0
	s_waitcnt lgkmcnt(3)
	v_mfma_f32_32x32x16_bf16 v[20:35], v[88:91], v[84:87], v[20:35]
	global_load_dwordx4 v[162:165], v242, s[30:31]
	ds_read_b128 v[100:103], v73 offset:4096
	s_waitcnt lgkmcnt(3)
	v_mfma_f32_32x32x16_bf16 v[36:51], v[92:95], v[80:83], v[36:51]
	ds_read_b128 v[108:111], v77 offset:4096
	v_mfma_f32_32x32x16_bf16 v[4:19], v[92:95], v[84:87], v[4:19]
	s_waitcnt lgkmcnt(2)
	v_mfma_f32_32x32x16_bf16 v[52:67], v[104:107], v[96:99], v[52:67]
	s_waitcnt lgkmcnt(1)
	v_mfma_f32_32x32x16_bf16 v[20:35], v[104:107], v[100:103], v[20:35]
	s_waitcnt lgkmcnt(0)
	v_mfma_f32_32x32x16_bf16 v[36:51], v[108:111], v[96:99], v[36:51]
	v_mfma_f32_32x32x16_bf16 v[4:19], v[108:111], v[100:103], v[4:19]
	s_waitcnt vmcnt(1)
	s_barrier
; template <int NI, bool DEEP = true>
; DEV void gemm_tile(f32x16 (&acc)[2][NI], const bf16* __restrict__ A, int lda, const bf16* __restrict__ Bt, int ldb,
;                    int K, bf16* sA, bf16* sB) {
;     ...
;   G_LOAD(ra0, rb0, 0)
;   if (DEEP) {
;     if (64 < K) G_LOAD(ra1, rb1, 64)
;     for (int k0 = 0; k0 < K; k0 += 128) {
;       G_STEP(ra0, rb0, k0 + 128)
;       if (k0 + 64 < K) G_STEP(ra1, rb1, k0 + 192)
;     }
; __device__ void phase_out(PRef p, int l, const bf16* M, const float* xl, const float* xc, bf16* sA, bf16* sB) {
;     ...
;       f32x4v x0 = *(const f32x4v*)xin, x1 = *(const f32x4v*)(xin + 4);
	ds_read_b128 v[88:91], v74 offset:38976
	ds_read_b128 v[80:83], v70 offset:32768
	ds_read_b128 v[84:87], v70 offset:36864
	ds_read_b128 v[92:95], v74 offset:43072
	s_waitcnt lgkmcnt(2)
	v_mfma_f32_32x32x16_bf16 v[52:67], v[88:91], v[80:83], v[52:67]
	s_add_u32 m0, s16, 0x0
	s_nop 0
	global_load_lds_dwordx4 v68, s[98:99]
	ds_read_b128 v[104:107], v75 offset:38976
	ds_read_b128 v[96:99], v71 offset:32768
	s_waitcnt lgkmcnt(3)
	v_mfma_f32_32x32x16_bf16 v[20:35], v[88:91], v[84:87], v[20:35]
	s_add_u32 m0, s16, 0x400
	s_add_u32 s14, s98, 0x4000
	s_addc_u32 s15, s99, 0
	global_load_lds_dwordx4 v69, s[14:15]
	ds_read_b128 v[100:103], v71 offset:36864
	s_waitcnt lgkmcnt(3)
	v_mfma_f32_32x32x16_bf16 v[36:51], v[92:95], v[80:83], v[36:51]
	s_add_u32 m0, s16, 0x800
	s_add_u32 s14, s98, 0x8000
	s_addc_u32 s15, s99, 0
	global_load_lds_dwordx4 v68, s[14:15]
	ds_read_b128 v[108:111], v75 offset:43072
	v_mfma_f32_32x32x16_bf16 v[4:19], v[92:95], v[84:87], v[4:19]
	s_add_u32 m0, s16, 0xc00
	s_add_u32 s14, s98, 0xc000
	s_addc_u32 s15, s99, 0
	global_load_lds_dwordx4 v69, s[14:15]
	s_waitcnt lgkmcnt(2)
	v_mfma_f32_32x32x16_bf16 v[52:67], v[104:107], v[96:99], v[52:67]
	s_add_u32 m0, s16, 0x4000
	s_nop 0
	global_load_lds_dwordx4 v68, s[100:101]
	ds_read_b128 v[88:91], v76 offset:38976
	ds_read_b128 v[80:83], v72 offset:32768
	s_waitcnt lgkmcnt(3)
	v_mfma_f32_32x32x16_bf16 v[20:35], v[104:107], v[100:103], v[20:35]
	s_add_u32 m0, s16, 0x4400
	s_add_u32 s14, s100, 0x4000
	s_addc_u32 s15, s101, 0
	global_load_lds_dwordx4 v69, s[14:15]
	ds_read_b128 v[84:87], v72 offset:36864
	s_waitcnt lgkmcnt(3)
	v_mfma_f32_32x32x16_bf16 v[36:51], v[108:111], v[96:99], v[36:51]
	s_add_u32 m0, s16, 0x4800
	s_add_u32 s14, s100, 0x8000
	s_addc_u32 s15, s101, 0
	global_load_lds_dwordx4 v68, s[14:15]
	ds_read_b128 v[92:95], v76 offset:43072
	v_mfma_f32_32x32x16_bf16 v[4:19], v[108:111], v[100:103], v[4:19]
	s_add_u32 m0, s16, 0x4c00
	s_add_u32 s14, s100, 0xc000
	s_addc_u32 s15, s101, 0
	global_load_lds_dwordx4 v69, s[14:15]
	s_waitcnt lgkmcnt(2)
	v_mfma_f32_32x32x16_bf16 v[52:67], v[88:91], v[80:83], v[52:67]
	s_add_u32 s98, s98, 0x80
	s_addc_u32 s99, s99, 0
	s_add_u32 s100, s100, 0x80
	s_addc_u32 s101, s101, 0
	ds_read_b128 v[104:107], v77 offset:38976
	ds_read_b128 v[96:99], v73 offset:32768
	s_waitcnt lgkmcnt(3)
	v_mfma_f32_32x32x16_bf16 v[20:35], v[88:91], v[84:87], v[20:35]
	global_load_dwordx4 v[166:169], v242, s[30:31] offset:16
	s_add_u32 s30, s30, 0x10000
	s_addc_u32 s31, s31, 0
	ds_read_b128 v[100:103], v73 offset:36864
	s_waitcnt lgkmcnt(3)
	v_mfma_f32_32x32x16_bf16 v[36:51], v[92:95], v[80:83], v[36:51]
	ds_read_b128 v[108:111], v77 offset:43072
	v_mfma_f32_32x32x16_bf16 v[4:19], v[92:95], v[84:87], v[4:19]
	s_waitcnt lgkmcnt(2)
	v_mfma_f32_32x32x16_bf16 v[52:67], v[104:107], v[96:99], v[52:67]
	s_waitcnt lgkmcnt(1)
	v_mfma_f32_32x32x16_bf16 v[20:35], v[104:107], v[100:103], v[20:35]
	s_waitcnt lgkmcnt(0)
	v_mfma_f32_32x32x16_bf16 v[36:51], v[108:111], v[96:99], v[36:51]
	v_mfma_f32_32x32x16_bf16 v[4:19], v[108:111], v[100:103], v[4:19]
	s_waitcnt vmcnt(1)
	s_barrier
	ds_read_b128 v[88:91], v74 offset:0
	ds_read_b128 v[80:83], v70 offset:0
	ds_read_b128 v[84:87], v70 offset:4096
	ds_read_b128 v[92:95], v74 offset:4096
	s_waitcnt lgkmcnt(2)
	v_mfma_f32_32x32x16_bf16 v[52:67], v[88:91], v[80:83], v[52:67]
	s_add_u32 m0, s16, 0x8000
	s_nop 0
	global_load_lds_dwordx4 v68, s[98:99]
	ds_read_b128 v[104:107], v75 offset:0
	ds_read_b128 v[96:99], v71 offset:0
	s_waitcnt lgkmcnt(3)
	v_mfma_f32_32x32x16_bf16 v[20:35], v[88:91], v[84:87], v[20:35]
	s_add_u32 m0, s16, 0x8400
	s_add_u32 s14, s98, 0x4000
	s_addc_u32 s15, s99, 0
	global_load_lds_dwordx4 v69, s[14:15]
	ds_read_b128 v[100:103], v71 offset:4096
	s_waitcnt lgkmcnt(3)
	v_mfma_f32_32x32x16_bf16 v[36:51], v[92:95], v[80:83], v[36:51]
	s_add_u32 m0, s16, 0x8800
	s_add_u32 s14, s98, 0x8000
	s_addc_u32 s15, s99, 0
	global_load_lds_dwordx4 v68, s[14:15]
	ds_read_b128 v[108:111], v75 offset:4096
	v_mfma_f32_32x32x16_bf16 v[4:19], v[92:95], v[84:87], v[4:19]
	s_add_u32 m0, s16, 0x8c00
	s_add_u32 s14, s98, 0xc000
	s_addc_u32 s15, s99, 0
	global_load_lds_dwordx4 v69, s[14:15]
	s_waitcnt lgkmcnt(2)
	v_mfma_f32_32x32x16_bf16 v[52:67], v[104:107], v[96:99], v[52:67]
	s_add_u32 m0, s16, 0xd840
	s_nop 0
	global_load_lds_dwordx4 v68, s[100:101]
	ds_read_b128 v[88:91], v76 offset:0
	ds_read_b128 v[80:83], v72 offset:0
	s_waitcnt lgkmcnt(3)
	v_mfma_f32_32x32x16_bf16 v[20:35], v[104:107], v[100:103], v[20:35]
	s_add_u32 m0, s16, 0xdc40
	s_add_u32 s14, s100, 0x4000
	s_addc_u32 s15, s101, 0
	global_load_lds_dwordx4 v69, s[14:15]
	ds_read_b128 v[84:87], v72 offset:4096
	s_waitcnt lgkmcnt(3)
	v_mfma_f32_32x32x16_bf16 v[36:51], v[108:111], v[96:99], v[36:51]
	s_add_u32 m0, s16, 0xe040
	s_add_u32 s14, s100, 0x8000
	s_addc_u32 s15, s101, 0
	global_load_lds_dwordx4 v68, s[14:15]
	ds_read_b128 v[92:95], v76 offset:4096
	v_mfma_f32_32x32x16_bf16 v[4:19], v[108:111], v[100:103], v[4:19]
	s_add_u32 m0, s16, 0xe440
	s_add_u32 s14, s100, 0xc000
	s_addc_u32 s15, s101, 0
	global_load_lds_dwordx4 v69, s[14:15]
	s_waitcnt lgkmcnt(2)
	v_mfma_f32_32x32x16_bf16 v[52:67], v[88:91], v[80:83], v[52:67]
	s_add_u32 s98, s98, 0x80
	s_addc_u32 s99, s99, 0
	s_add_u32 s100, s100, 0x80
	s_addc_u32 s101, s101, 0
	ds_read_b128 v[104:107], v77 offset:0
	ds_read_b128 v[96:99], v73 offset:0
	s_waitcnt lgkmcnt(3)
	v_mfma_f32_32x32x16_bf16 v[20:35], v[88:91], v[84:87], v[20:35]
	global_load_dwordx4 v[170:173], v242, s[30:31]
	ds_read_b128 v[100:103], v73 offset:4096
	s_waitcnt lgkmcnt(3)
	v_mfma_f32_32x32x16_bf16 v[36:51], v[92:95], v[80:83], v[36:51]
	ds_read_b128 v[108:111], v77 offset:4096
	v_mfma_f32_32x32x16_bf16 v[4:19], v[92:95], v[84:87], v[4:19]
	s_waitcnt lgkmcnt(2)
	v_mfma_f32_32x32x16_bf16 v[52:67], v[104:107], v[96:99], v[52:67]
	s_waitcnt lgkmcnt(1)
	v_mfma_f32_32x32x16_bf16 v[20:35], v[104:107], v[100:103], v[20:35]
	s_waitcnt lgkmcnt(0)
	v_mfma_f32_32x32x16_bf16 v[36:51], v[108:111], v[96:99], v[36:51]
	v_mfma_f32_32x32x16_bf16 v[4:19], v[108:111], v[100:103], v[4:19]
	s_waitcnt vmcnt(1)
	s_barrier
; template <int NI, bool DEEP = true>
; DEV void gemm_tile(f32x16 (&acc)[2][NI], const bf16* __restrict__ A, int lda, const bf16* __restrict__ Bt, int ldb,
;                    int K, bf16* sA, bf16* sB) {
;     ...
;   G_LOAD(ra0, rb0, 0)
;   if (DEEP) {
;     if (64 < K) G_LOAD(ra1, rb1, 64)
;     for (int k0 = 0; k0 < K; k0 += 128) {
;       G_STEP(ra0, rb0, k0 + 128)
;       if (k0 + 64 < K) G_STEP(ra1, rb1, k0 + 192)
;     }
; __device__ void phase_out(PRef p, int l, const bf16* M, const float* xl, const float* xc, bf16* sA, bf16* sB) {
;     ...
;       f32x4v x0 = *(const f32x4v*)xin, x1 = *(const f32x4v*)(xin + 4);
	ds_read_b128 v[88:91], v74 offset:38976
	ds_read_b128 v[80:83], v70 offset:32768
	ds_read_b128 v[84:87], v70 offset:36864
	ds_read_b128 v[92:95], v74 offset:43072
	s_waitcnt lgkmcnt(2)
	v_mfma_f32_32x32x16_bf16 v[52:67], v[88:91], v[80:83], v[52:67]
	s_add_u32 m0, s16, 0x0
	s_nop 0
	global_load_lds_dwordx4 v68, s[98:99]
	ds_read_b128 v[104:107], v75 offset:38976
	ds_read_b128 v[96:99], v71 offset:32768
	s_waitcnt lgkmcnt(3)
	v_mfma_f32_32x32x16_bf16 v[20:35], v[88:91], v[84:87], v[20:35]
	s_add_u32 m0, s16, 0x400
	s_add_u32 s14, s98, 0x4000
	s_addc_u32 s15, s99, 0
	global_load_lds_dwordx4 v69, s[14:15]
	ds_read_b128 v[100:103], v71 offset:36864
	s_waitcnt lgkmcnt(3)
	v_mfma_f32_32x32x16_bf16 v[36:51], v[92:95], v[80:83], v[36:51]
	s_add_u32 m0, s16, 0x800
	s_add_u32 s14, s98, 0x8000
	s_addc_u32 s15, s99, 0
	global_load_lds_dwordx4 v68, s[14:15]
	ds_read_b128 v[108:111], v75 offset:43072
	v_mfma_f32_32x32x16_bf16 v[4:19], v[92:95], v[84:87], v[4:19]
	s_add_u32 m0, s16, 0xc00
	s_add_u32 s14, s98, 0xc000
	s_addc_u32 s15, s99, 0
	global_load_lds_dwordx4 v69, s[14:15]
	s_waitcnt lgkmcnt(2)
	v_mfma_f32_32x32x16_bf16 v[52:67], v[104:107], v[96:99], v[52:67]
	s_add_u32 m0, s16, 0x4000
	s_nop 0
	global_load_lds_dwordx4 v68, s[100:101]
	ds_read_b128 v[88:91], v76 offset:38976
	ds_read_b128 v[80:83], v72 offset:32768
	s_waitcnt lgkmcnt(3)
	v_mfma_f32_32x32x16_bf16 v[20:35], v[104:107], v[100:103], v[20:35]
	s_add_u32 m0, s16, 0x4400
	s_add_u32 s14, s100, 0x4000
	s_addc_u32 s15, s101, 0
	global_load_lds_dwordx4 v69, s[14:15]
	ds_read_b128 v[84:87], v72 offset:36864
	s_waitcnt lgkmcnt(3)
	v_mfma_f32_32x32x16_bf16 v[36:51], v[108:111], v[96:99], v[36:51]
	s_add_u32 m0, s16, 0x4800
	s_add_u32 s14, s100, 0x8000
	s_addc_u32 s15, s101, 0
	global_load_lds_dwordx4 v68, s[14:15]
	ds_read_b128 v[92:95], v76 offset:43072
	v_mfma_f32_32x32x16_bf16 v[4:19], v[108:111], v[100:103], v[4:19]
	s_add_u32 m0, s16, 0x4c00
	s_add_u32 s14, s100, 0xc000
	s_addc_u32 s15, s101, 0
	global_load_lds_dwordx4 v69, s[14:15]
	s_waitcnt lgkmcnt(2)
	v_mfma_f32_32x32x16_bf16 v[52:67], v[88:91], v[80:83], v[52:67]
	s_add_u32 s98, s98, 0x80
	s_addc_u32 s99, s99, 0
	s_add_u32 s100, s100, 0x80
	s_addc_u32 s101, s101, 0
	ds_read_b128 v[104:107], v77 offset:38976
	ds_read_b128 v[96:99], v73 offset:32768
	s_waitcnt lgkmcnt(3)
	v_mfma_f32_32x32x16_bf16 v[20:35], v[88:91], v[84:87], v[20:35]
	global_load_dwordx4 v[174:177], v242, s[30:31] offset:16
	s_add_u32 s30, s30, 0x10000
	s_addc_u32 s31, s31, 0
	ds_read_b128 v[100:103], v73 offset:36864
	s_waitcnt lgkmcnt(3)
	v_mfma_f32_32x32x16_bf16 v[36:51], v[92:95], v[80:83], v[36:51]
	ds_read_b128 v[108:111], v77 offset:43072
	v_mfma_f32_32x32x16_bf16 v[4:19], v[92:95], v[84:87], v[4:19]
	s_waitcnt lgkmcnt(2)
	v_mfma_f32_32x32x16_bf16 v[52:67], v[104:107], v[96:99], v[52:67]
	s_waitcnt lgkmcnt(1)
	v_mfma_f32_32x32x16_bf16 v[20:35], v[104:107], v[100:103], v[20:35]
	s_waitcnt lgkmcnt(0)
	v_mfma_f32_32x32x16_bf16 v[36:51], v[108:111], v[96:99], v[36:51]
	v_mfma_f32_32x32x16_bf16 v[4:19], v[108:111], v[100:103], v[4:19]
	s_waitcnt vmcnt(1)
	s_barrier
	ds_read_b128 v[88:91], v74 offset:0
	ds_read_b128 v[80:83], v70 offset:0
	ds_read_b128 v[84:87], v70 offset:4096
	ds_read_b128 v[92:95], v74 offset:4096
	s_waitcnt lgkmcnt(2)
	v_mfma_f32_32x32x16_bf16 v[52:67], v[88:91], v[80:83], v[52:67]
	s_add_u32 m0, s16, 0x8000
	s_nop 0
	global_load_lds_dwordx4 v68, s[98:99]
	ds_read_b128 v[104:107], v75 offset:0
	ds_read_b128 v[96:99], v71 offset:0
	s_waitcnt lgkmcnt(3)
	v_mfma_f32_32x32x16_bf16 v[20:35], v[88:91], v[84:87], v[20:35]
	s_add_u32 m0, s16, 0x8400
	s_add_u32 s14, s98, 0x4000
	s_addc_u32 s15, s99, 0
	global_load_lds_dwordx4 v69, s[14:15]
	ds_read_b128 v[100:103], v71 offset:4096
	s_waitcnt lgkmcnt(3)
	v_mfma_f32_32x32x16_bf16 v[36:51], v[92:95], v[80:83], v[36:51]
	s_add_u32 m0, s16, 0x8800
	s_add_u32 s14, s98, 0x8000
	s_addc_u32 s15, s99, 0
	global_load_lds_dwordx4 v68, s[14:15]
	ds_read_b128 v[108:111], v75 offset:4096
	v_mfma_f32_32x32x16_bf16 v[4:19], v[92:95], v[84:87], v[4:19]
	s_add_u32 m0, s16, 0x8c00
	s_add_u32 s14, s98, 0xc000
	s_addc_u32 s15, s99, 0
	global_load_lds_dwordx4 v69, s[14:15]
	s_waitcnt lgkmcnt(2)
	v_mfma_f32_32x32x16_bf16 v[52:67], v[104:107], v[96:99], v[52:67]
	s_add_u32 m0, s16, 0xd840
	s_nop 0
	global_load_lds_dwordx4 v68, s[100:101]
	ds_read_b128 v[88:91], v76 offset:0
	ds_read_b128 v[80:83], v72 offset:0
	s_waitcnt lgkmcnt(3)
	v_mfma_f32_32x32x16_bf16 v[20:35], v[104:107], v[100:103], v[20:35]
	s_add_u32 m0, s16, 0xdc40
	s_add_u32 s14, s100, 0x4000
	s_addc_u32 s15, s101, 0
	global_load_lds_dwordx4 v69, s[14:15]
	ds_read_b128 v[84:87], v72 offset:4096
	s_waitcnt lgkmcnt(3)
	v_mfma_f32_32x32x16_bf16 v[36:51], v[108:111], v[96:99], v[36:51]
	s_add_u32 m0, s16, 0xe040
	s_add_u32 s14, s100, 0x8000
	s_addc_u32 s15, s101, 0
	global_load_lds_dwordx4 v68, s[14:15]
	ds_read_b128 v[92:95], v76 offset:4096
	v_mfma_f32_32x32x16_bf16 v[4:19], v[108:111], v[100:103], v[4:19]
	s_add_u32 m0, s16, 0xe440
	s_add_u32 s14, s100, 0xc000
	s_addc_u32 s15, s101, 0
	global_load_lds_dwordx4 v69, s[14:15]
	s_waitcnt lgkmcnt(2)
	v_mfma_f32_32x32x16_bf16 v[52:67], v[88:91], v[80:83], v[52:67]
	s_add_u32 s98, s98, 0x80
	s_addc_u32 s99, s99, 0
	s_add_u32 s100, s100, 0x80
	s_addc_u32 s101, s101, 0
	ds_read_b128 v[104:107], v77 offset:0
	ds_read_b128 v[96:99], v73 offset:0
	s_waitcnt lgkmcnt(3)
	v_mfma_f32_32x32x16_bf16 v[20:35], v[88:91], v[84:87], v[20:35]
	global_load_dwordx4 v[178:181], v242, s[30:31]
	ds_read_b128 v[100:103], v73 offset:4096
	s_waitcnt lgkmcnt(3)
	v_mfma_f32_32x32x16_bf16 v[36:51], v[92:95], v[80:83], v[36:51]
	ds_read_b128 v[108:111], v77 offset:4096
	v_mfma_f32_32x32x16_bf16 v[4:19], v[92:95], v[84:87], v[4:19]
	s_waitcnt lgkmcnt(2)
	v_mfma_f32_32x32x16_bf16 v[52:67], v[104:107], v[96:99], v[52:67]
	s_waitcnt lgkmcnt(1)
	v_mfma_f32_32x32x16_bf16 v[20:35], v[104:107], v[100:103], v[20:35]
	s_waitcnt lgkmcnt(0)
	v_mfma_f32_32x32x16_bf16 v[36:51], v[108:111], v[96:99], v[36:51]
	v_mfma_f32_32x32x16_bf16 v[4:19], v[108:111], v[100:103], v[4:19]
	s_waitcnt vmcnt(1)
	s_barrier
; __device__ void phase_out(PRef p, int l, const bf16* M, const float* xl, const float* xc, bf16* sA, bf16* sB) {
;     ...
;       f32x4v x0 = *(const f32x4v*)xin, x1 = *(const f32x4v*)(xin + 4);
	ds_read_b128 v[88:91], v74 offset:38976
	ds_read_b128 v[80:83], v70 offset:32768
	ds_read_b128 v[84:87], v70 offset:36864
	ds_read_b128 v[92:95], v74 offset:43072
	s_waitcnt lgkmcnt(2)
	v_mfma_f32_32x32x16_bf16 v[52:67], v[88:91], v[80:83], v[52:67]
	s_add_u32 m0, s16, 0x0
	s_nop 0
	global_load_lds_dwordx4 v68, s[98:99]
	ds_read_b128 v[104:107], v75 offset:38976
	ds_read_b128 v[96:99], v71 offset:32768
	s_waitcnt lgkmcnt(3)
	v_mfma_f32_32x32x16_bf16 v[20:35], v[88:91], v[84:87], v[20:35]
	s_add_u32 m0, s16, 0x400
	s_add_u32 s14, s98, 0x4000
	s_addc_u32 s15, s99, 0
	global_load_lds_dwordx4 v69, s[14:15]
	ds_read_b128 v[100:103], v71 offset:36864
	s_waitcnt lgkmcnt(3)
	v_mfma_f32_32x32x16_bf16 v[36:51], v[92:95], v[80:83], v[36:51]
	s_add_u32 m0, s16, 0x800
	s_add_u32 s14, s98, 0x8000
	s_addc_u32 s15, s99, 0
	global_load_lds_dwordx4 v68, s[14:15]
	ds_read_b128 v[108:111], v75 offset:43072
	v_mfma_f32_32x32x16_bf16 v[4:19], v[92:95], v[84:87], v[4:19]
	s_add_u32 m0, s16, 0xc00
	s_add_u32 s14, s98, 0xc000
	s_addc_u32 s15, s99, 0
	global_load_lds_dwordx4 v69, s[14:15]
	s_waitcnt lgkmcnt(2)
	v_mfma_f32_32x32x16_bf16 v[52:67], v[104:107], v[96:99], v[52:67]
	s_add_u32 m0, s16, 0x4000
	s_nop 0
	global_load_lds_dwordx4 v68, s[100:101]
	ds_read_b128 v[88:91], v76 offset:38976
	ds_read_b128 v[80:83], v72 offset:32768
	s_waitcnt lgkmcnt(3)
	v_mfma_f32_32x32x16_bf16 v[20:35], v[104:107], v[100:103], v[20:35]
	s_add_u32 m0, s16, 0x4400
	s_add_u32 s14, s100, 0x4000
	s_addc_u32 s15, s101, 0
	global_load_lds_dwordx4 v69, s[14:15]
	ds_read_b128 v[84:87], v72 offset:36864
	s_waitcnt lgkmcnt(3)
	v_mfma_f32_32x32x16_bf16 v[36:51], v[108:111], v[96:99], v[36:51]
	s_add_u32 m0, s16, 0x4800
	s_add_u32 s14, s100, 0x8000
	s_addc_u32 s15, s101, 0
	global_load_lds_dwordx4 v68, s[14:15]
	ds_read_b128 v[92:95], v76 offset:43072
	v_mfma_f32_32x32x16_bf16 v[4:19], v[108:111], v[100:103], v[4:19]
	s_add_u32 m0, s16, 0x4c00
	s_add_u32 s14, s100, 0xc000
	s_addc_u32 s15, s101, 0
	global_load_lds_dwordx4 v69, s[14:15]
	s_waitcnt lgkmcnt(2)
	v_mfma_f32_32x32x16_bf16 v[52:67], v[88:91], v[80:83], v[52:67]
	s_add_u32 s98, s98, 0x80
	s_addc_u32 s99, s99, 0
	s_add_u32 s100, s100, 0x80
	s_addc_u32 s101, s101, 0
	ds_read_b128 v[104:107], v77 offset:38976
	ds_read_b128 v[96:99], v73 offset:32768
	s_waitcnt lgkmcnt(3)
	v_mfma_f32_32x32x16_bf16 v[20:35], v[88:91], v[84:87], v[20:35]
	global_load_dwordx4 v[182:185], v242, s[30:31] offset:16
	s_add_u32 s30, s30, 0x10000
	s_addc_u32 s31, s31, 0
	ds_read_b128 v[100:103], v73 offset:36864
	s_waitcnt lgkmcnt(3)
	v_mfma_f32_32x32x16_bf16 v[36:51], v[92:95], v[80:83], v[36:51]
	ds_read_b128 v[108:111], v77 offset:43072
	v_mfma_f32_32x32x16_bf16 v[4:19], v[92:95], v[84:87], v[4:19]
	s_waitcnt lgkmcnt(2)
	v_mfma_f32_32x32x16_bf16 v[52:67], v[104:107], v[96:99], v[52:67]
	s_waitcnt lgkmcnt(1)
	v_mfma_f32_32x32x16_bf16 v[20:35], v[104:107], v[100:103], v[20:35]
	s_waitcnt lgkmcnt(0)
	v_mfma_f32_32x32x16_bf16 v[36:51], v[108:111], v[96:99], v[36:51]
	v_mfma_f32_32x32x16_bf16 v[4:19], v[108:111], v[100:103], v[4:19]
	s_waitcnt vmcnt(1)
	s_barrier
	ds_read_b128 v[88:91], v74 offset:0
	ds_read_b128 v[80:83], v70 offset:0
	ds_read_b128 v[84:87], v70 offset:4096
	ds_read_b128 v[92:95], v74 offset:4096
	s_waitcnt lgkmcnt(2)
	v_mfma_f32_32x32x16_bf16 v[52:67], v[88:91], v[80:83], v[52:67]
	s_add_u32 m0, s16, 0x8000
	s_nop 0
	global_load_lds_dwordx4 v68, s[98:99]
	ds_read_b128 v[104:107], v75 offset:0
	ds_read_b128 v[96:99], v71 offset:0
	s_waitcnt lgkmcnt(3)
	v_mfma_f32_32x32x16_bf16 v[20:35], v[88:91], v[84:87], v[20:35]
	s_add_u32 m0, s16, 0x8400
	s_add_u32 s14, s98, 0x4000
	s_addc_u32 s15, s99, 0
	global_load_lds_dwordx4 v69, s[14:15]
	ds_read_b128 v[100:103], v71 offset:4096
	s_waitcnt lgkmcnt(3)
	v_mfma_f32_32x32x16_bf16 v[36:51], v[92:95], v[80:83], v[36:51]
	s_add_u32 m0, s16, 0x8800
	s_add_u32 s14, s98, 0x8000
	s_addc_u32 s15, s99, 0
	global_load_lds_dwordx4 v68, s[14:15]
	ds_read_b128 v[108:111], v75 offset:4096
	v_mfma_f32_32x32x16_bf16 v[4:19], v[92:95], v[84:87], v[4:19]
	s_add_u32 m0, s16, 0x8c00
	s_add_u32 s14, s98, 0xc000
	s_addc_u32 s15, s99, 0
	global_load_lds_dwordx4 v69, s[14:15]
	s_waitcnt lgkmcnt(2)
	v_mfma_f32_32x32x16_bf16 v[52:67], v[104:107], v[96:99], v[52:67]
	s_add_u32 m0, s16, 0xd840
	s_nop 0
	global_load_lds_dwordx4 v68, s[100:101]
	ds_read_b128 v[88:91], v76 offset:0
	ds_read_b128 v[80:83], v72 offset:0
	s_waitcnt lgkmcnt(3)
	v_mfma_f32_32x32x16_bf16 v[20:35], v[104:107], v[100:103], v[20:35]
	s_add_u32 m0, s16, 0xdc40
	s_add_u32 s14, s100, 0x4000
	s_addc_u32 s15, s101, 0
	global_load_lds_dwordx4 v69, s[14:15]
	ds_read_b128 v[84:87], v72 offset:4096
	s_waitcnt lgkmcnt(3)
	v_mfma_f32_32x32x16_bf16 v[36:51], v[108:111], v[96:99], v[36:51]
	s_add_u32 m0, s16, 0xe040
	s_add_u32 s14, s100, 0x8000
	s_addc_u32 s15, s101, 0
	global_load_lds_dwordx4 v68, s[14:15]
	ds_read_b128 v[92:95], v76 offset:4096
	v_mfma_f32_32x32x16_bf16 v[4:19], v[108:111], v[100:103], v[4:19]
	s_add_u32 m0, s16, 0xe440
	s_add_u32 s14, s100, 0xc000
	s_addc_u32 s15, s101, 0
	global_load_lds_dwordx4 v69, s[14:15]
	s_waitcnt lgkmcnt(2)
	v_mfma_f32_32x32x16_bf16 v[52:67], v[88:91], v[80:83], v[52:67]
	s_add_u32 s98, s98, 0x80
	s_addc_u32 s99, s99, 0
	s_add_u32 s100, s100, 0x80
	s_addc_u32 s101, s101, 0
	ds_read_b128 v[104:107], v77 offset:0
	ds_read_b128 v[96:99], v73 offset:0
	s_waitcnt lgkmcnt(3)
	v_mfma_f32_32x32x16_bf16 v[20:35], v[88:91], v[84:87], v[20:35]
	global_load_dwordx4 v[186:189], v242, s[30:31]
	ds_read_b128 v[100:103], v73 offset:4096
	s_waitcnt lgkmcnt(3)
	v_mfma_f32_32x32x16_bf16 v[36:51], v[92:95], v[80:83], v[36:51]
	ds_read_b128 v[108:111], v77 offset:4096
	v_mfma_f32_32x32x16_bf16 v[4:19], v[92:95], v[84:87], v[4:19]
	s_waitcnt lgkmcnt(2)
	v_mfma_f32_32x32x16_bf16 v[52:67], v[104:107], v[96:99], v[52:67]
	s_waitcnt lgkmcnt(1)
	v_mfma_f32_32x32x16_bf16 v[20:35], v[104:107], v[100:103], v[20:35]
	s_waitcnt lgkmcnt(0)
	v_mfma_f32_32x32x16_bf16 v[36:51], v[108:111], v[96:99], v[36:51]
	v_mfma_f32_32x32x16_bf16 v[4:19], v[108:111], v[100:103], v[4:19]
	s_waitcnt vmcnt(1)
	s_barrier
; __device__ void phase_out(PRef p, int l, const bf16* M, const float* xl, const float* xc, bf16* sA, bf16* sB) {
;     ...
;       f32x4v x0 = *(const f32x4v*)xin, x1 = *(const f32x4v*)(xin + 4);
	ds_read_b128 v[88:91], v74 offset:38976
	ds_read_b128 v[80:83], v70 offset:32768
	ds_read_b128 v[84:87], v70 offset:36864
	ds_read_b128 v[92:95], v74 offset:43072
	s_waitcnt lgkmcnt(2)
	v_mfma_f32_32x32x16_bf16 v[52:67], v[88:91], v[80:83], v[52:67]
	s_add_u32 m0, s16, 0x0
	s_nop 0
	global_load_lds_dwordx4 v68, s[98:99]
	ds_read_b128 v[104:107], v75 offset:38976
	ds_read_b128 v[96:99], v71 offset:32768
	s_waitcnt lgkmcnt(3)
	v_mfma_f32_32x32x16_bf16 v[20:35], v[88:91], v[84:87], v[20:35]
	s_add_u32 m0, s16, 0x400
	s_add_u32 s14, s98, 0x4000
	s_addc_u32 s15, s99, 0
	global_load_lds_dwordx4 v69, s[14:15]
	ds_read_b128 v[100:103], v71 offset:36864
	s_waitcnt lgkmcnt(3)
	v_mfma_f32_32x32x16_bf16 v[36:51], v[92:95], v[80:83], v[36:51]
	s_add_u32 m0, s16, 0x800
	s_add_u32 s14, s98, 0x8000
	s_addc_u32 s15, s99, 0
	global_load_lds_dwordx4 v68, s[14:15]
	ds_read_b128 v[108:111], v75 offset:43072
	v_mfma_f32_32x32x16_bf16 v[4:19], v[92:95], v[84:87], v[4:19]
	s_add_u32 m0, s16, 0xc00
	s_add_u32 s14, s98, 0xc000
	s_addc_u32 s15, s99, 0
	global_load_lds_dwordx4 v69, s[14:15]
	s_waitcnt lgkmcnt(2)
	v_mfma_f32_32x32x16_bf16 v[52:67], v[104:107], v[96:99], v[52:67]
	s_add_u32 m0, s16, 0x4000
	s_nop 0
	global_load_lds_dwordx4 v68, s[100:101]
	ds_read_b128 v[88:91], v76 offset:38976
	ds_read_b128 v[80:83], v72 offset:32768
	s_waitcnt lgkmcnt(3)
	v_mfma_f32_32x32x16_bf16 v[20:35], v[104:107], v[100:103], v[20:35]
	s_add_u32 m0, s16, 0x4400
	s_add_u32 s14, s100, 0x4000
	s_addc_u32 s15, s101, 0
	global_load_lds_dwordx4 v69, s[14:15]
	ds_read_b128 v[84:87], v72 offset:36864
	s_waitcnt lgkmcnt(3)
	v_mfma_f32_32x32x16_bf16 v[36:51], v[108:111], v[96:99], v[36:51]
	s_add_u32 m0, s16, 0x4800
	s_add_u32 s14, s100, 0x8000
	s_addc_u32 s15, s101, 0
	global_load_lds_dwordx4 v68, s[14:15]
	ds_read_b128 v[92:95], v76 offset:43072
	v_mfma_f32_32x32x16_bf16 v[4:19], v[108:111], v[100:103], v[4:19]
	s_add_u32 m0, s16, 0x4c00
	s_add_u32 s14, s100, 0xc000
	s_addc_u32 s15, s101, 0
	global_load_lds_dwordx4 v69, s[14:15]
	s_waitcnt lgkmcnt(2)
	v_mfma_f32_32x32x16_bf16 v[52:67], v[88:91], v[80:83], v[52:67]
	s_add_u32 s98, s98, 0x80
	s_addc_u32 s99, s99, 0
	s_add_u32 s100, s100, 0x80
	s_addc_u32 s101, s101, 0
	ds_read_b128 v[104:107], v77 offset:38976
	ds_read_b128 v[96:99], v73 offset:32768
	s_waitcnt lgkmcnt(3)
	v_mfma_f32_32x32x16_bf16 v[20:35], v[88:91], v[84:87], v[20:35]
	global_load_dwordx4 v[190:193], v242, s[30:31] offset:16
	s_add_u32 s30, s30, 0x10000
	s_addc_u32 s31, s31, 0
	ds_read_b128 v[100:103], v73 offset:36864
	s_waitcnt lgkmcnt(3)
	v_mfma_f32_32x32x16_bf16 v[36:51], v[92:95], v[80:83], v[36:51]
	ds_read_b128 v[108:111], v77 offset:43072
	v_mfma_f32_32x32x16_bf16 v[4:19], v[92:95], v[84:87], v[4:19]
	s_waitcnt lgkmcnt(2)
	v_mfma_f32_32x32x16_bf16 v[52:67], v[104:107], v[96:99], v[52:67]
	s_waitcnt lgkmcnt(1)
	v_mfma_f32_32x32x16_bf16 v[20:35], v[104:107], v[100:103], v[20:35]
	s_waitcnt lgkmcnt(0)
	v_mfma_f32_32x32x16_bf16 v[36:51], v[108:111], v[96:99], v[36:51]
	v_mfma_f32_32x32x16_bf16 v[4:19], v[108:111], v[100:103], v[4:19]
	s_waitcnt vmcnt(1)
	s_barrier
	ds_read_b128 v[88:91], v74 offset:0
	ds_read_b128 v[80:83], v70 offset:0
	ds_read_b128 v[84:87], v70 offset:4096
	ds_read_b128 v[92:95], v74 offset:4096
	s_waitcnt lgkmcnt(2)
	v_mfma_f32_32x32x16_bf16 v[52:67], v[88:91], v[80:83], v[52:67]
	s_add_u32 m0, s16, 0x8000
	s_nop 0
	global_load_lds_dwordx4 v68, s[98:99]
	ds_read_b128 v[104:107], v75 offset:0
	ds_read_b128 v[96:99], v71 offset:0
	s_waitcnt lgkmcnt(3)
	v_mfma_f32_32x32x16_bf16 v[20:35], v[88:91], v[84:87], v[20:35]
	s_add_u32 m0, s16, 0x8400
	s_add_u32 s14, s98, 0x4000
	s_addc_u32 s15, s99, 0
	global_load_lds_dwordx4 v69, s[14:15]
	ds_read_b128 v[100:103], v71 offset:4096
	s_waitcnt lgkmcnt(3)
	v_mfma_f32_32x32x16_bf16 v[36:51], v[92:95], v[80:83], v[36:51]
	s_add_u32 m0, s16, 0x8800
	s_add_u32 s14, s98, 0x8000
	s_addc_u32 s15, s99, 0
	global_load_lds_dwordx4 v68, s[14:15]
	ds_read_b128 v[108:111], v75 offset:4096
	v_mfma_f32_32x32x16_bf16 v[4:19], v[92:95], v[84:87], v[4:19]
	s_add_u32 m0, s16, 0x8c00
	s_add_u32 s14, s98, 0xc000
	s_addc_u32 s15, s99, 0
	global_load_lds_dwordx4 v69, s[14:15]
	s_waitcnt lgkmcnt(2)
	v_mfma_f32_32x32x16_bf16 v[52:67], v[104:107], v[96:99], v[52:67]
	s_add_u32 m0, s16, 0xd840
	s_nop 0
	global_load_lds_dwordx4 v68, s[100:101]
	ds_read_b128 v[88:91], v76 offset:0
	ds_read_b128 v[80:83], v72 offset:0
	s_waitcnt lgkmcnt(3)
	v_mfma_f32_32x32x16_bf16 v[20:35], v[104:107], v[100:103], v[20:35]
	s_add_u32 m0, s16, 0xdc40
	s_add_u32 s14, s100, 0x4000
	s_addc_u32 s15, s101, 0
	global_load_lds_dwordx4 v69, s[14:15]
	ds_read_b128 v[84:87], v72 offset:4096
	s_waitcnt lgkmcnt(3)
	v_mfma_f32_32x32x16_bf16 v[36:51], v[108:111], v[96:99], v[36:51]
	s_add_u32 m0, s16, 0xe040
	s_add_u32 s14, s100, 0x8000
	s_addc_u32 s15, s101, 0
	global_load_lds_dwordx4 v68, s[14:15]
	ds_read_b128 v[92:95], v76 offset:4096
	v_mfma_f32_32x32x16_bf16 v[4:19], v[108:111], v[100:103], v[4:19]
	s_add_u32 m0, s16, 0xe440
	s_add_u32 s14, s100, 0xc000
	s_addc_u32 s15, s101, 0
	global_load_lds_dwordx4 v69, s[14:15]
	s_waitcnt lgkmcnt(2)
	v_mfma_f32_32x32x16_bf16 v[52:67], v[88:91], v[80:83], v[52:67]
	s_add_u32 s98, s98, 0x80
	s_addc_u32 s99, s99, 0
	s_add_u32 s100, s100, 0x80
	s_addc_u32 s101, s101, 0
	ds_read_b128 v[104:107], v77 offset:0
	ds_read_b128 v[96:99], v73 offset:0
	s_waitcnt lgkmcnt(3)
	v_mfma_f32_32x32x16_bf16 v[20:35], v[88:91], v[84:87], v[20:35]
	global_load_dwordx4 v[210:213], v242, s[30:31]
	ds_read_b128 v[100:103], v73 offset:4096
	s_waitcnt lgkmcnt(3)
	v_mfma_f32_32x32x16_bf16 v[36:51], v[92:95], v[80:83], v[36:51]
	ds_read_b128 v[108:111], v77 offset:4096
	v_mfma_f32_32x32x16_bf16 v[4:19], v[92:95], v[84:87], v[4:19]
	s_waitcnt lgkmcnt(2)
	v_mfma_f32_32x32x16_bf16 v[52:67], v[104:107], v[96:99], v[52:67]
	s_waitcnt lgkmcnt(1)
	v_mfma_f32_32x32x16_bf16 v[20:35], v[104:107], v[100:103], v[20:35]
	s_waitcnt lgkmcnt(0)
	v_mfma_f32_32x32x16_bf16 v[36:51], v[108:111], v[96:99], v[36:51]
	v_mfma_f32_32x32x16_bf16 v[4:19], v[108:111], v[100:103], v[4:19]
	s_waitcnt vmcnt(1)
	s_barrier
; __device__ void phase_out(PRef p, int l, const bf16* M, const float* xl, const float* xc, bf16* sA, bf16* sB) {
;     ...
;       f32x4v x0 = *(const f32x4v*)xin, x1 = *(const f32x4v*)(xin + 4);
	ds_read_b128 v[88:91], v74 offset:38976
	ds_read_b128 v[80:83], v70 offset:32768
	ds_read_b128 v[84:87], v70 offset:36864
	ds_read_b128 v[92:95], v74 offset:43072
	s_waitcnt lgkmcnt(2)
	v_mfma_f32_32x32x16_bf16 v[52:67], v[88:91], v[80:83], v[52:67]
	s_add_u32 m0, s16, 0x0
	s_nop 0
	global_load_lds_dwordx4 v68, s[98:99]
	ds_read_b128 v[104:107], v75 offset:38976
	ds_read_b128 v[96:99], v71 offset:32768
	s_waitcnt lgkmcnt(3)
	v_mfma_f32_32x32x16_bf16 v[20:35], v[88:91], v[84:87], v[20:35]
	s_add_u32 m0, s16, 0x400
	s_add_u32 s14, s98, 0x4000
	s_addc_u32 s15, s99, 0
	global_load_lds_dwordx4 v69, s[14:15]
	ds_read_b128 v[100:103], v71 offset:36864
	s_waitcnt lgkmcnt(3)
	v_mfma_f32_32x32x16_bf16 v[36:51], v[92:95], v[80:83], v[36:51]
	s_add_u32 m0, s16, 0x800
	s_add_u32 s14, s98, 0x8000
	s_addc_u32 s15, s99, 0
	global_load_lds_dwordx4 v68, s[14:15]
	ds_read_b128 v[108:111], v75 offset:43072
	v_mfma_f32_32x32x16_bf16 v[4:19], v[92:95], v[84:87], v[4:19]
	s_add_u32 m0, s16, 0xc00
	s_add_u32 s14, s98, 0xc000
	s_addc_u32 s15, s99, 0
	global_load_lds_dwordx4 v69, s[14:15]
	s_waitcnt lgkmcnt(2)
	v_mfma_f32_32x32x16_bf16 v[52:67], v[104:107], v[96:99], v[52:67]
	s_add_u32 m0, s16, 0x4000
	s_nop 0
	global_load_lds_dwordx4 v68, s[100:101]
	ds_read_b128 v[88:91], v76 offset:38976
	ds_read_b128 v[80:83], v72 offset:32768
	s_waitcnt lgkmcnt(3)
	v_mfma_f32_32x32x16_bf16 v[20:35], v[104:107], v[100:103], v[20:35]
	s_add_u32 m0, s16, 0x4400
	s_add_u32 s14, s100, 0x4000
	s_addc_u32 s15, s101, 0
	global_load_lds_dwordx4 v69, s[14:15]
	ds_read_b128 v[84:87], v72 offset:36864
	s_waitcnt lgkmcnt(3)
	v_mfma_f32_32x32x16_bf16 v[36:51], v[108:111], v[96:99], v[36:51]
	s_add_u32 m0, s16, 0x4800
	s_add_u32 s14, s100, 0x8000
	s_addc_u32 s15, s101, 0
	global_load_lds_dwordx4 v68, s[14:15]
	ds_read_b128 v[92:95], v76 offset:43072
	v_mfma_f32_32x32x16_bf16 v[4:19], v[108:111], v[100:103], v[4:19]
	s_add_u32 m0, s16, 0x4c00
	s_add_u32 s14, s100, 0xc000
	s_addc_u32 s15, s101, 0
	global_load_lds_dwordx4 v69, s[14:15]
	s_waitcnt lgkmcnt(2)
	v_mfma_f32_32x32x16_bf16 v[52:67], v[88:91], v[80:83], v[52:67]
	s_add_u32 s98, s98, 0x80
	s_addc_u32 s99, s99, 0
	s_add_u32 s100, s100, 0x80
	s_addc_u32 s101, s101, 0
	ds_read_b128 v[104:107], v77 offset:38976
	ds_read_b128 v[96:99], v73 offset:32768
	s_waitcnt lgkmcnt(3)
	v_mfma_f32_32x32x16_bf16 v[20:35], v[88:91], v[84:87], v[20:35]
	global_load_dwordx4 v[214:217], v242, s[30:31] offset:16
	s_add_u32 s30, s30, 0x10000
	s_addc_u32 s31, s31, 0
	ds_read_b128 v[100:103], v73 offset:36864
	s_waitcnt lgkmcnt(3)
	v_mfma_f32_32x32x16_bf16 v[36:51], v[92:95], v[80:83], v[36:51]
	ds_read_b128 v[108:111], v77 offset:43072
	v_mfma_f32_32x32x16_bf16 v[4:19], v[92:95], v[84:87], v[4:19]
	s_waitcnt lgkmcnt(2)
	v_mfma_f32_32x32x16_bf16 v[52:67], v[104:107], v[96:99], v[52:67]
	s_waitcnt lgkmcnt(1)
	v_mfma_f32_32x32x16_bf16 v[20:35], v[104:107], v[100:103], v[20:35]
	s_waitcnt lgkmcnt(0)
	v_mfma_f32_32x32x16_bf16 v[36:51], v[108:111], v[96:99], v[36:51]
	v_mfma_f32_32x32x16_bf16 v[4:19], v[108:111], v[100:103], v[4:19]
	s_waitcnt vmcnt(1)
	s_barrier
	ds_read_b128 v[88:91], v74 offset:0
	ds_read_b128 v[80:83], v70 offset:0
	ds_read_b128 v[84:87], v70 offset:4096
	ds_read_b128 v[92:95], v74 offset:4096
	s_waitcnt lgkmcnt(2)
	v_mfma_f32_32x32x16_bf16 v[52:67], v[88:91], v[80:83], v[52:67]
	s_add_u32 m0, s16, 0x8000
	s_nop 0
	global_load_lds_dwordx4 v68, s[98:99]
	ds_read_b128 v[104:107], v75 offset:0
	ds_read_b128 v[96:99], v71 offset:0
	s_waitcnt lgkmcnt(3)
	v_mfma_f32_32x32x16_bf16 v[20:35], v[88:91], v[84:87], v[20:35]
	s_add_u32 m0, s16, 0x8400
	s_add_u32 s14, s98, 0x4000
	s_addc_u32 s15, s99, 0
	global_load_lds_dwordx4 v69, s[14:15]
	ds_read_b128 v[100:103], v71 offset:4096
	s_waitcnt lgkmcnt(3)
	v_mfma_f32_32x32x16_bf16 v[36:51], v[92:95], v[80:83], v[36:51]
	s_add_u32 m0, s16, 0x8800
	s_add_u32 s14, s98, 0x8000
	s_addc_u32 s15, s99, 0
	global_load_lds_dwordx4 v68, s[14:15]
	ds_read_b128 v[108:111], v75 offset:4096
	v_mfma_f32_32x32x16_bf16 v[4:19], v[92:95], v[84:87], v[4:19]
	s_add_u32 m0, s16, 0x8c00
	s_add_u32 s14, s98, 0xc000
	s_addc_u32 s15, s99, 0
	global_load_lds_dwordx4 v69, s[14:15]
	s_waitcnt lgkmcnt(2)
	v_mfma_f32_32x32x16_bf16 v[52:67], v[104:107], v[96:99], v[52:67]
	s_add_u32 m0, s16, 0xd840
	s_nop 0
	global_load_lds_dwordx4 v68, s[100:101]
	ds_read_b128 v[88:91], v76 offset:0
	ds_read_b128 v[80:83], v72 offset:0
	s_waitcnt lgkmcnt(3)
	v_mfma_f32_32x32x16_bf16 v[20:35], v[104:107], v[100:103], v[20:35]
	s_add_u32 m0, s16, 0xdc40
	s_add_u32 s14, s100, 0x4000
	s_addc_u32 s15, s101, 0
	global_load_lds_dwordx4 v69, s[14:15]
	ds_read_b128 v[84:87], v72 offset:4096
	s_waitcnt lgkmcnt(3)
	v_mfma_f32_32x32x16_bf16 v[36:51], v[108:111], v[96:99], v[36:51]
	s_add_u32 m0, s16, 0xe040
	s_add_u32 s14, s100, 0x8000
	s_addc_u32 s15, s101, 0
	global_load_lds_dwordx4 v68, s[14:15]
	ds_read_b128 v[92:95], v76 offset:4096
	v_mfma_f32_32x32x16_bf16 v[4:19], v[108:111], v[100:103], v[4:19]
	s_add_u32 m0, s16, 0xe440
	s_add_u32 s14, s100, 0xc000
	s_addc_u32 s15, s101, 0
	global_load_lds_dwordx4 v69, s[14:15]
	s_waitcnt lgkmcnt(2)
	v_mfma_f32_32x32x16_bf16 v[52:67], v[88:91], v[80:83], v[52:67]
	s_add_u32 s98, s98, 0x80
	s_addc_u32 s99, s99, 0
	s_add_u32 s100, s100, 0x80
	s_addc_u32 s101, s101, 0
	ds_read_b128 v[104:107], v77 offset:0
	ds_read_b128 v[96:99], v73 offset:0
	s_waitcnt lgkmcnt(3)
	v_mfma_f32_32x32x16_bf16 v[20:35], v[88:91], v[84:87], v[20:35]
	global_load_dwordx4 v[218:221], v242, s[30:31]
	ds_read_b128 v[100:103], v73 offset:4096
	s_waitcnt lgkmcnt(3)
	v_mfma_f32_32x32x16_bf16 v[36:51], v[92:95], v[80:83], v[36:51]
	ds_read_b128 v[108:111], v77 offset:4096
	v_mfma_f32_32x32x16_bf16 v[4:19], v[92:95], v[84:87], v[4:19]
	s_waitcnt lgkmcnt(2)
	v_mfma_f32_32x32x16_bf16 v[52:67], v[104:107], v[96:99], v[52:67]
	s_waitcnt lgkmcnt(1)
	v_mfma_f32_32x32x16_bf16 v[20:35], v[104:107], v[100:103], v[20:35]
	s_waitcnt lgkmcnt(0)
	v_mfma_f32_32x32x16_bf16 v[36:51], v[108:111], v[96:99], v[36:51]
	v_mfma_f32_32x32x16_bf16 v[4:19], v[108:111], v[100:103], v[4:19]
	s_waitcnt vmcnt(1)
	s_barrier
; __device__ void phase_out(PRef p, int l, const bf16* M, const float* xl, const float* xc, bf16* sA, bf16* sB) {
;     ...
;       f32x4v x0 = *(const f32x4v*)xin, x1 = *(const f32x4v*)(xin + 4);
	ds_read_b128 v[88:91], v74 offset:38976
	ds_read_b128 v[80:83], v70 offset:32768
	ds_read_b128 v[84:87], v70 offset:36864
	ds_read_b128 v[92:95], v74 offset:43072
	s_waitcnt lgkmcnt(2)
	v_mfma_f32_32x32x16_bf16 v[52:67], v[88:91], v[80:83], v[52:67]
	s_add_u32 m0, s16, 0x0
	s_nop 0
	global_load_lds_dwordx4 v68, s[98:99]
	ds_read_b128 v[104:107], v75 offset:38976
	ds_read_b128 v[96:99], v71 offset:32768
	s_waitcnt lgkmcnt(3)
	v_mfma_f32_32x32x16_bf16 v[20:35], v[88:91], v[84:87], v[20:35]
	s_add_u32 m0, s16, 0x400
	s_add_u32 s14, s98, 0x4000
	s_addc_u32 s15, s99, 0
	global_load_lds_dwordx4 v69, s[14:15]
	ds_read_b128 v[100:103], v71 offset:36864
	s_waitcnt lgkmcnt(3)
	v_mfma_f32_32x32x16_bf16 v[36:51], v[92:95], v[80:83], v[36:51]
	s_add_u32 m0, s16, 0x800
	s_add_u32 s14, s98, 0x8000
	s_addc_u32 s15, s99, 0
	global_load_lds_dwordx4 v68, s[14:15]
	ds_read_b128 v[108:111], v75 offset:43072
	v_mfma_f32_32x32x16_bf16 v[4:19], v[92:95], v[84:87], v[4:19]
	s_add_u32 m0, s16, 0xc00
	s_add_u32 s14, s98, 0xc000
	s_addc_u32 s15, s99, 0
	global_load_lds_dwordx4 v69, s[14:15]
	s_waitcnt lgkmcnt(2)
	v_mfma_f32_32x32x16_bf16 v[52:67], v[104:107], v[96:99], v[52:67]
	s_add_u32 m0, s16, 0x4000
	s_nop 0
	global_load_lds_dwordx4 v68, s[100:101]
	ds_read_b128 v[88:91], v76 offset:38976
	ds_read_b128 v[80:83], v72 offset:32768
	s_waitcnt lgkmcnt(3)
	v_mfma_f32_32x32x16_bf16 v[20:35], v[104:107], v[100:103], v[20:35]
	s_add_u32 m0, s16, 0x4400
	s_add_u32 s14, s100, 0x4000
	s_addc_u32 s15, s101, 0
	global_load_lds_dwordx4 v69, s[14:15]
	ds_read_b128 v[84:87], v72 offset:36864
	s_waitcnt lgkmcnt(3)
	v_mfma_f32_32x32x16_bf16 v[36:51], v[108:111], v[96:99], v[36:51]
	s_add_u32 m0, s16, 0x4800
	s_add_u32 s14, s100, 0x8000
	s_addc_u32 s15, s101, 0
	global_load_lds_dwordx4 v68, s[14:15]
	ds_read_b128 v[92:95], v76 offset:43072
	v_mfma_f32_32x32x16_bf16 v[4:19], v[108:111], v[100:103], v[4:19]
	s_add_u32 m0, s16, 0x4c00
	s_add_u32 s14, s100, 0xc000
	s_addc_u32 s15, s101, 0
	global_load_lds_dwordx4 v69, s[14:15]
	s_waitcnt lgkmcnt(2)
	v_mfma_f32_32x32x16_bf16 v[52:67], v[88:91], v[80:83], v[52:67]
	s_add_u32 s98, s98, 0x80
	s_addc_u32 s99, s99, 0
	s_add_u32 s100, s100, 0x80
	s_addc_u32 s101, s101, 0
	ds_read_b128 v[104:107], v77 offset:38976
	ds_read_b128 v[96:99], v73 offset:32768
	s_waitcnt lgkmcnt(3)
	v_mfma_f32_32x32x16_bf16 v[20:35], v[88:91], v[84:87], v[20:35]
	global_load_dwordx4 v[222:225], v242, s[30:31] offset:16
	s_add_u32 s30, s30, 0x10000
	s_addc_u32 s31, s31, 0
	ds_read_b128 v[100:103], v73 offset:36864
	s_waitcnt lgkmcnt(3)
	v_mfma_f32_32x32x16_bf16 v[36:51], v[92:95], v[80:83], v[36:51]
	ds_read_b128 v[108:111], v77 offset:43072
	v_mfma_f32_32x32x16_bf16 v[4:19], v[92:95], v[84:87], v[4:19]
	s_waitcnt lgkmcnt(2)
	v_mfma_f32_32x32x16_bf16 v[52:67], v[104:107], v[96:99], v[52:67]
	s_waitcnt lgkmcnt(1)
	v_mfma_f32_32x32x16_bf16 v[20:35], v[104:107], v[100:103], v[20:35]
	s_waitcnt lgkmcnt(0)
	v_mfma_f32_32x32x16_bf16 v[36:51], v[108:111], v[96:99], v[36:51]
	v_mfma_f32_32x32x16_bf16 v[4:19], v[108:111], v[100:103], v[4:19]
	s_waitcnt vmcnt(1)
	s_barrier
	ds_read_b128 v[88:91], v74 offset:0
	ds_read_b128 v[80:83], v70 offset:0
	ds_read_b128 v[84:87], v70 offset:4096
	ds_read_b128 v[92:95], v74 offset:4096
	s_waitcnt lgkmcnt(2)
	v_mfma_f32_32x32x16_bf16 v[52:67], v[88:91], v[80:83], v[52:67]
	s_add_u32 m0, s16, 0x8000
	s_nop 0
	global_load_lds_dwordx4 v68, s[98:99]
	ds_read_b128 v[104:107], v75 offset:0
	ds_read_b128 v[96:99], v71 offset:0
	s_waitcnt lgkmcnt(3)
	v_mfma_f32_32x32x16_bf16 v[20:35], v[88:91], v[84:87], v[20:35]
	s_add_u32 m0, s16, 0x8400
	s_add_u32 s14, s98, 0x4000
	s_addc_u32 s15, s99, 0
	global_load_lds_dwordx4 v69, s[14:15]
	ds_read_b128 v[100:103], v71 offset:4096
	s_waitcnt lgkmcnt(3)
	v_mfma_f32_32x32x16_bf16 v[36:51], v[92:95], v[80:83], v[36:51]
	s_add_u32 m0, s16, 0x8800
	s_add_u32 s14, s98, 0x8000
	s_addc_u32 s15, s99, 0
	global_load_lds_dwordx4 v68, s[14:15]
	ds_read_b128 v[108:111], v75 offset:4096
	v_mfma_f32_32x32x16_bf16 v[4:19], v[92:95], v[84:87], v[4:19]
	s_add_u32 m0, s16, 0x8c00
	s_add_u32 s14, s98, 0xc000
	s_addc_u32 s15, s99, 0
	global_load_lds_dwordx4 v69, s[14:15]
	s_waitcnt lgkmcnt(2)
	v_mfma_f32_32x32x16_bf16 v[52:67], v[104:107], v[96:99], v[52:67]
	s_add_u32 m0, s16, 0xd840
	s_nop 0
	global_load_lds_dwordx4 v68, s[100:101]
	ds_read_b128 v[88:91], v76 offset:0
	ds_read_b128 v[80:83], v72 offset:0
	s_waitcnt lgkmcnt(3)
	v_mfma_f32_32x32x16_bf16 v[20:35], v[104:107], v[100:103], v[20:35]
	s_add_u32 m0, s16, 0xdc40
	s_add_u32 s14, s100, 0x4000
	s_addc_u32 s15, s101, 0
	global_load_lds_dwordx4 v69, s[14:15]
	ds_read_b128 v[84:87], v72 offset:4096
	s_waitcnt lgkmcnt(3)
	v_mfma_f32_32x32x16_bf16 v[36:51], v[108:111], v[96:99], v[36:51]
	s_add_u32 m0, s16, 0xe040
	s_add_u32 s14, s100, 0x8000
	s_addc_u32 s15, s101, 0
	global_load_lds_dwordx4 v68, s[14:15]
	ds_read_b128 v[92:95], v76 offset:4096
	v_mfma_f32_32x32x16_bf16 v[4:19], v[108:111], v[100:103], v[4:19]
	s_add_u32 m0, s16, 0xe440
	s_add_u32 s14, s100, 0xc000
	s_addc_u32 s15, s101, 0
	global_load_lds_dwordx4 v69, s[14:15]
	s_waitcnt lgkmcnt(2)
	v_mfma_f32_32x32x16_bf16 v[52:67], v[88:91], v[80:83], v[52:67]
	s_add_u32 s98, s98, 0x80
	s_addc_u32 s99, s99, 0
	s_add_u32 s100, s100, 0x80
	s_addc_u32 s101, s101, 0
	ds_read_b128 v[104:107], v77 offset:0
	ds_read_b128 v[96:99], v73 offset:0
	s_waitcnt lgkmcnt(3)
	v_mfma_f32_32x32x16_bf16 v[20:35], v[88:91], v[84:87], v[20:35]
	global_load_dwordx4 v[226:229], v242, s[30:31]
	ds_read_b128 v[100:103], v73 offset:4096
	s_waitcnt lgkmcnt(3)
	v_mfma_f32_32x32x16_bf16 v[36:51], v[92:95], v[80:83], v[36:51]
	ds_read_b128 v[108:111], v77 offset:4096
	v_mfma_f32_32x32x16_bf16 v[4:19], v[92:95], v[84:87], v[4:19]
	s_waitcnt lgkmcnt(2)
	v_mfma_f32_32x32x16_bf16 v[52:67], v[104:107], v[96:99], v[52:67]
	s_waitcnt lgkmcnt(1)
	v_mfma_f32_32x32x16_bf16 v[20:35], v[104:107], v[100:103], v[20:35]
	s_waitcnt lgkmcnt(0)
	v_mfma_f32_32x32x16_bf16 v[36:51], v[108:111], v[96:99], v[36:51]
	v_mfma_f32_32x32x16_bf16 v[4:19], v[108:111], v[100:103], v[4:19]
	s_waitcnt vmcnt(1)
	s_barrier
; __device__ void phase_out(PRef p, int l, const bf16* M, const float* xl, const float* xc, bf16* sA, bf16* sB) {
;     ...
;       f32x4v x0 = *(const f32x4v*)xin, x1 = *(const f32x4v*)(xin + 4);
	ds_read_b128 v[88:91], v74 offset:38976
	ds_read_b128 v[80:83], v70 offset:32768
	ds_read_b128 v[84:87], v70 offset:36864
	ds_read_b128 v[92:95], v74 offset:43072
	s_waitcnt lgkmcnt(2)
	v_mfma_f32_32x32x16_bf16 v[52:67], v[88:91], v[80:83], v[52:67]
	s_add_u32 m0, s16, 0x0
	s_nop 0
	global_load_lds_dwordx4 v68, s[98:99]
	ds_read_b128 v[104:107], v75 offset:38976
	ds_read_b128 v[96:99], v71 offset:32768
	s_waitcnt lgkmcnt(3)
	v_mfma_f32_32x32x16_bf16 v[20:35], v[88:91], v[84:87], v[20:35]
	s_add_u32 m0, s16, 0x400
	s_add_u32 s14, s98, 0x4000
	s_addc_u32 s15, s99, 0
	global_load_lds_dwordx4 v69, s[14:15]
	ds_read_b128 v[100:103], v71 offset:36864
	s_waitcnt lgkmcnt(3)
	v_mfma_f32_32x32x16_bf16 v[36:51], v[92:95], v[80:83], v[36:51]
	s_add_u32 m0, s16, 0x800
	s_add_u32 s14, s98, 0x8000
	s_addc_u32 s15, s99, 0
	global_load_lds_dwordx4 v68, s[14:15]
	ds_read_b128 v[108:111], v75 offset:43072
	v_mfma_f32_32x32x16_bf16 v[4:19], v[92:95], v[84:87], v[4:19]
	s_add_u32 m0, s16, 0xc00
	s_add_u32 s14, s98, 0xc000
	s_addc_u32 s15, s99, 0
	global_load_lds_dwordx4 v69, s[14:15]
	s_waitcnt lgkmcnt(2)
	v_mfma_f32_32x32x16_bf16 v[52:67], v[104:107], v[96:99], v[52:67]
	s_add_u32 m0, s16, 0x4000
	s_nop 0
	global_load_lds_dwordx4 v68, s[100:101]
	ds_read_b128 v[88:91], v76 offset:38976
	ds_read_b128 v[80:83], v72 offset:32768
	s_waitcnt lgkmcnt(3)
	v_mfma_f32_32x32x16_bf16 v[20:35], v[104:107], v[100:103], v[20:35]
	s_add_u32 m0, s16, 0x4400
	s_add_u32 s14, s100, 0x4000
	s_addc_u32 s15, s101, 0
	global_load_lds_dwordx4 v69, s[14:15]
	ds_read_b128 v[84:87], v72 offset:36864
	s_waitcnt lgkmcnt(3)
	v_mfma_f32_32x32x16_bf16 v[36:51], v[108:111], v[96:99], v[36:51]
	s_add_u32 m0, s16, 0x4800
	s_add_u32 s14, s100, 0x8000
	s_addc_u32 s15, s101, 0
	global_load_lds_dwordx4 v68, s[14:15]
	ds_read_b128 v[92:95], v76 offset:43072
	v_mfma_f32_32x32x16_bf16 v[4:19], v[108:111], v[100:103], v[4:19]
	s_add_u32 m0, s16, 0x4c00
	s_add_u32 s14, s100, 0xc000
	s_addc_u32 s15, s101, 0
	global_load_lds_dwordx4 v69, s[14:15]
	s_waitcnt lgkmcnt(2)
	v_mfma_f32_32x32x16_bf16 v[52:67], v[88:91], v[80:83], v[52:67]
	s_add_u32 s98, s98, 0x80
	s_addc_u32 s99, s99, 0
	s_add_u32 s100, s100, 0x80
	s_addc_u32 s101, s101, 0
	ds_read_b128 v[104:107], v77 offset:38976
	ds_read_b128 v[96:99], v73 offset:32768
	s_waitcnt lgkmcnt(3)
	v_mfma_f32_32x32x16_bf16 v[20:35], v[88:91], v[84:87], v[20:35]
	global_load_dwordx4 v[230:233], v242, s[30:31] offset:16
	s_add_u32 s30, s30, 0x10000
	s_addc_u32 s31, s31, 0
	ds_read_b128 v[100:103], v73 offset:36864
	s_waitcnt lgkmcnt(3)
	v_mfma_f32_32x32x16_bf16 v[36:51], v[92:95], v[80:83], v[36:51]
	ds_read_b128 v[108:111], v77 offset:43072
	v_mfma_f32_32x32x16_bf16 v[4:19], v[92:95], v[84:87], v[4:19]
	s_waitcnt lgkmcnt(2)
	v_mfma_f32_32x32x16_bf16 v[52:67], v[104:107], v[96:99], v[52:67]
	s_waitcnt lgkmcnt(1)
	v_mfma_f32_32x32x16_bf16 v[20:35], v[104:107], v[100:103], v[20:35]
	s_waitcnt lgkmcnt(0)
	v_mfma_f32_32x32x16_bf16 v[36:51], v[108:111], v[96:99], v[36:51]
	v_mfma_f32_32x32x16_bf16 v[4:19], v[108:111], v[100:103], v[4:19]
	s_waitcnt vmcnt(1)
	s_barrier
	ds_read_b128 v[88:91], v74 offset:0
	ds_read_b128 v[80:83], v70 offset:0
	ds_read_b128 v[84:87], v70 offset:4096
	ds_read_b128 v[92:95], v74 offset:4096
	s_waitcnt lgkmcnt(2)
	v_mfma_f32_32x32x16_bf16 v[52:67], v[88:91], v[80:83], v[52:67]
	s_add_u32 m0, s16, 0x8000
	s_nop 0
	global_load_lds_dwordx4 v68, s[98:99]
	ds_read_b128 v[104:107], v75 offset:0
	ds_read_b128 v[96:99], v71 offset:0
	s_waitcnt lgkmcnt(3)
	v_mfma_f32_32x32x16_bf16 v[20:35], v[88:91], v[84:87], v[20:35]
	s_add_u32 m0, s16, 0x8400
	s_add_u32 s14, s98, 0x4000
	s_addc_u32 s15, s99, 0
	global_load_lds_dwordx4 v69, s[14:15]
	ds_read_b128 v[100:103], v71 offset:4096
	s_waitcnt lgkmcnt(3)
	v_mfma_f32_32x32x16_bf16 v[36:51], v[92:95], v[80:83], v[36:51]
	s_add_u32 m0, s16, 0x8800
	s_add_u32 s14, s98, 0x8000
	s_addc_u32 s15, s99, 0
	global_load_lds_dwordx4 v68, s[14:15]
	ds_read_b128 v[108:111], v75 offset:4096
	v_mfma_f32_32x32x16_bf16 v[4:19], v[92:95], v[84:87], v[4:19]
	s_add_u32 m0, s16, 0x8c00
	s_add_u32 s14, s98, 0xc000
	s_addc_u32 s15, s99, 0
	global_load_lds_dwordx4 v69, s[14:15]
	s_waitcnt lgkmcnt(2)
	v_mfma_f32_32x32x16_bf16 v[52:67], v[104:107], v[96:99], v[52:67]
	s_add_u32 m0, s16, 0xd840
	s_nop 0
	global_load_lds_dwordx4 v68, s[100:101]
	ds_read_b128 v[88:91], v76 offset:0
	ds_read_b128 v[80:83], v72 offset:0
	s_waitcnt lgkmcnt(3)
	v_mfma_f32_32x32x16_bf16 v[20:35], v[104:107], v[100:103], v[20:35]
	s_add_u32 m0, s16, 0xdc40
	s_add_u32 s14, s100, 0x4000
	s_addc_u32 s15, s101, 0
	global_load_lds_dwordx4 v69, s[14:15]
	ds_read_b128 v[84:87], v72 offset:4096
	s_waitcnt lgkmcnt(3)
	v_mfma_f32_32x32x16_bf16 v[36:51], v[108:111], v[96:99], v[36:51]
	s_add_u32 m0, s16, 0xe040
	s_add_u32 s14, s100, 0x8000
	s_addc_u32 s15, s101, 0
	global_load_lds_dwordx4 v68, s[14:15]
	ds_read_b128 v[92:95], v76 offset:4096
	v_mfma_f32_32x32x16_bf16 v[4:19], v[108:111], v[100:103], v[4:19]
	s_add_u32 m0, s16, 0xe440
	s_add_u32 s14, s100, 0xc000
	s_addc_u32 s15, s101, 0
	global_load_lds_dwordx4 v69, s[14:15]
	s_waitcnt lgkmcnt(2)
	v_mfma_f32_32x32x16_bf16 v[52:67], v[88:91], v[80:83], v[52:67]
	s_add_u32 s98, s98, 0x80
	s_addc_u32 s99, s99, 0
	s_add_u32 s100, s100, 0x80
	s_addc_u32 s101, s101, 0
	ds_read_b128 v[104:107], v77 offset:0
	ds_read_b128 v[96:99], v73 offset:0
	s_waitcnt lgkmcnt(3)
	v_mfma_f32_32x32x16_bf16 v[20:35], v[88:91], v[84:87], v[20:35]
	global_load_dwordx4 v[234:237], v242, s[30:31]
	ds_read_b128 v[100:103], v73 offset:4096
	s_waitcnt lgkmcnt(3)
	v_mfma_f32_32x32x16_bf16 v[36:51], v[92:95], v[80:83], v[36:51]
	ds_read_b128 v[108:111], v77 offset:4096
	v_mfma_f32_32x32x16_bf16 v[4:19], v[92:95], v[84:87], v[4:19]
	s_waitcnt lgkmcnt(2)
	v_mfma_f32_32x32x16_bf16 v[52:67], v[104:107], v[96:99], v[52:67]
	s_waitcnt lgkmcnt(1)
	v_mfma_f32_32x32x16_bf16 v[20:35], v[104:107], v[100:103], v[20:35]
	s_waitcnt lgkmcnt(0)
	v_mfma_f32_32x32x16_bf16 v[36:51], v[108:111], v[96:99], v[36:51]
	v_mfma_f32_32x32x16_bf16 v[4:19], v[108:111], v[100:103], v[4:19]
	s_waitcnt vmcnt(1)
	s_barrier
; DEV int tid_() { int t = threadIdx.x; asm volatile("" : "+v"(t)); return t; }
; template <int NI>
; DEV void stage_tile(const f32x16 (&acc)[2][NI], bf16* sC) {
;   constexpr int LDC = NI * 64 + 8;
;   int tid = tid_();
;   int lane = tid & 63, wave = tid >> 6;
;   int wm = wave >> 1, wn = wave & 1;
;   __syncthreads();
; #pragma unroll
;   for (int mi = 0; mi < 2; mi++)
; #pragma unroll
;     for (int ni = 0; ni < NI; ni++)
; #pragma unroll
;       for (int g = 0; g < 4; g++) {
;         int row = wm * 64 + mi * 32 + (lane & 31);
;         int col = wn * NI * 32 + ni * 32 + 8 * g + 4 * (lane >> 5);
;         uint2 v;
;         v.x = pack2(acc[mi][ni][4 * g], acc[mi][ni][4 * g + 1]);
;         v.y = pack2(acc[mi][ni][4 * g + 2], acc[mi][ni][4 * g + 3]);
;         *(uint2*)(sC + row * LDC + col) = v;
;       }
;   __syncthreads();
; }
	ds_read_b128 v[88:91], v74 offset:38976
	ds_read_b128 v[80:83], v70 offset:32768
	ds_read_b128 v[84:87], v70 offset:36864
	ds_read_b128 v[92:95], v74 offset:43072
	s_waitcnt lgkmcnt(2)
	v_mfma_f32_32x32x16_bf16 v[52:67], v[88:91], v[80:83], v[52:67]
	global_load_dwordx4 v[238:241], v242, s[30:31] offset:16
	ds_read_b128 v[104:107], v75 offset:38976
	ds_read_b128 v[96:99], v71 offset:32768
	s_waitcnt lgkmcnt(3)
	v_mfma_f32_32x32x16_bf16 v[20:35], v[88:91], v[84:87], v[20:35]
	ds_read_b128 v[100:103], v71 offset:36864
	s_waitcnt lgkmcnt(3)
	v_mfma_f32_32x32x16_bf16 v[36:51], v[92:95], v[80:83], v[36:51]
	ds_read_b128 v[108:111], v75 offset:43072
	v_mfma_f32_32x32x16_bf16 v[4:19], v[92:95], v[84:87], v[4:19]
	s_waitcnt lgkmcnt(2)
	v_mfma_f32_32x32x16_bf16 v[52:67], v[104:107], v[96:99], v[52:67]
	ds_read_b128 v[88:91], v76 offset:38976
	ds_read_b128 v[80:83], v72 offset:32768
	s_waitcnt lgkmcnt(3)
	v_mfma_f32_32x32x16_bf16 v[20:35], v[104:107], v[100:103], v[20:35]
	ds_read_b128 v[84:87], v72 offset:36864
	s_waitcnt lgkmcnt(3)
	v_mfma_f32_32x32x16_bf16 v[36:51], v[108:111], v[96:99], v[36:51]
	ds_read_b128 v[92:95], v76 offset:43072
	v_mfma_f32_32x32x16_bf16 v[4:19], v[108:111], v[100:103], v[4:19]
	s_waitcnt lgkmcnt(2)
	v_mfma_f32_32x32x16_bf16 v[52:67], v[88:91], v[80:83], v[52:67]
	ds_read_b128 v[104:107], v77 offset:38976
	ds_read_b128 v[96:99], v73 offset:32768
	s_waitcnt lgkmcnt(3)
	v_mfma_f32_32x32x16_bf16 v[20:35], v[88:91], v[84:87], v[20:35]
	ds_read_b128 v[100:103], v73 offset:36864
	s_waitcnt lgkmcnt(3)
	v_mfma_f32_32x32x16_bf16 v[36:51], v[92:95], v[80:83], v[36:51]
	ds_read_b128 v[108:111], v77 offset:43072
	v_mfma_f32_32x32x16_bf16 v[4:19], v[92:95], v[84:87], v[4:19]
	s_waitcnt lgkmcnt(2)
	v_mfma_f32_32x32x16_bf16 v[52:67], v[104:107], v[96:99], v[52:67]
	s_waitcnt lgkmcnt(1)
	v_mfma_f32_32x32x16_bf16 v[20:35], v[104:107], v[100:103], v[20:35]
	s_waitcnt lgkmcnt(0)
	v_mfma_f32_32x32x16_bf16 v[36:51], v[108:111], v[96:99], v[36:51]
	v_mfma_f32_32x32x16_bf16 v[4:19], v[108:111], v[100:103], v[4:19]
	s_nop 7
	s_nop 7
.LBB0_1089:
	v_mov_b32_e32 v0, v196
	s_nop 5
	v_cvt_pk_bf16_f32 v52, v52, v53
	v_lshrrev_b32_e32 v1, 1, v0
	v_and_b32_e32 v2, 31, v0
	v_and_or_b32 v1, v1, s75, v2
	v_and_b32_e32 v2, 64, v0
	v_lshrrev_b32_e32 v0, 2, v0
	v_and_b32_e32 v0, 8, v0
	v_lshl_or_b32 v0, v2, 1, v0
	v_mad_u64_u32 v[0:1], s[14:15], v1, s52, v[0:1]
	v_cvt_pk_bf16_f32 v53, v54, v55
	v_cvt_pk_bf16_f32 v54, v56, v57
	v_cvt_pk_bf16_f32 v55, v58, v59
	v_cvt_pk_bf16_f32 v36, v36, v37
	v_cvt_pk_bf16_f32 v37, v38, v39
	v_cvt_pk_bf16_f32 v38, v40, v41
	v_cvt_pk_bf16_f32 v39, v42, v43
	s_barrier
	ds_write2_b64 v0, v[52:53], v[54:55] offset1:2
	v_cvt_pk_bf16_f32 v52, v60, v61
	v_cvt_pk_bf16_f32 v53, v62, v63
	v_cvt_pk_bf16_f32 v54, v64, v65
	v_cvt_pk_bf16_f32 v55, v66, v67
	ds_write2_b64 v0, v[36:37], v[38:39] offset0:8 offset1:10
	v_cvt_pk_bf16_f32 v36, v44, v45
	v_cvt_pk_bf16_f32 v37, v46, v47
	v_cvt_pk_bf16_f32 v38, v48, v49
	v_cvt_pk_bf16_f32 v39, v50, v51
	v_cvt_pk_bf16_f32 v20, v20, v21
	v_cvt_pk_bf16_f32 v21, v22, v23
	v_cvt_pk_bf16_f32 v22, v24, v25
	v_cvt_pk_bf16_f32 v23, v26, v27
	v_add_u32_e32 v2, 0x2000, v0
	ds_write2_b64 v0, v[52:53], v[54:55] offset0:4 offset1:6
	ds_write2_b64 v0, v[36:37], v[38:39] offset0:12 offset1:14
	ds_write2_b64 v2, v[20:21], v[22:23] offset0:64 offset1:66
	v_cvt_pk_bf16_f32 v0, v28, v29
	v_cvt_pk_bf16_f32 v1, v30, v31
	v_cvt_pk_bf16_f32 v20, v32, v33
	v_cvt_pk_bf16_f32 v21, v34, v35
	ds_write2_b64 v2, v[0:1], v[20:21] offset0:68 offset1:70
	v_cvt_pk_bf16_f32 v0, v4, v5
	v_cvt_pk_bf16_f32 v1, v6, v7
	v_cvt_pk_bf16_f32 v4, v8, v9
	v_cvt_pk_bf16_f32 v5, v10, v11
	ds_write2_b64 v2, v[0:1], v[4:5] offset0:72 offset1:74
	v_cvt_pk_bf16_f32 v0, v12, v13
	v_cvt_pk_bf16_f32 v1, v14, v15
	v_cvt_pk_bf16_f32 v4, v16, v17
	v_cvt_pk_bf16_f32 v5, v18, v19
	ds_write2_b64 v2, v[0:1], v[4:5] offset0:76 offset1:78
	v_mov_b32_e32 v2, v196
	s_waitcnt lgkmcnt(0)
	s_barrier
; __device__ void phase_out(PRef p, int l, const bf16* M, const float* xl, const float* xc, bf16* sA, bf16* sB) {
;     ...
;     int b = rt / 18;
;     bool isctx = (rt % 18) < 2;
;     const float* gate = p.MOD + ((size_t)l * 17 + (isctx ? 16 : b)) * 3072 + 2048;
;     stage_tile<2>(acc, sA);
;     TILE_CHUNKS(2, sA, {
;       int R = rt * 128 + trow;
;       int col = ct * 128 + tcol;
;       int tp = R % TPB;
;       const float* xin;
;       float* dstp;
;       if (isctx) {
;         xin = xc + ((size_t)b * 256 + tp) * 1024 + col;
;         dstp = p.XC + ((size_t)b * 256 + tp) * 1024 + col;
;       } else {
;         xin = xl + ((size_t)b * 2048 + (tp - 256)) * 1024 + col;
;         dstp = p.out + ((size_t)b * 2048 + (tp - 256)) * 1024 + col;
;       }
;       f32x4v x0 = *(const f32x4v*)xin, x1 = *(const f32x4v*)(xin + 4);
;       f32x4v g0 = *(const f32x4v*)(gate + col), g1 = *(const f32x4v*)(gate + col + 4);
;       f32x4v o0, o1;
;       o0.x = x0.x + g0.x * __uint_as_float(cv[0] << 16);
;       o0.y = x0.y + g0.y * __uint_as_float(cv[0] & 0xffff0000u);
;       o0.z = x0.z + g0.z * __uint_as_float(cv[1] << 16);
;       o0.w = x0.w + g0.w * __uint_as_float(cv[1] & 0xffff0000u);
;       o1.x = x1.x + g1.x * __uint_as_float(cv[2] << 16);
;       o1.y = x1.y + g1.y * __uint_as_float(cv[2] & 0xffff0000u);
;       o1.z = x1.z + g1.z * __uint_as_float(cv[3] << 16);
;       o1.w = x1.w + g1.w * __uint_as_float(cv[3] & 0xffff0000u);
;       *(f32x4v*)dstp = o0;
;       *(f32x4v*)(dstp + 4) = o1;
;     })
	s_lshl_b32 s14, s20, 9
	s_and_b64 s[22:23], s[22:23], exec
	s_cselect_b32 s18, 16, s18
	s_ashr_i32 s19, s18, 31
	s_add_u32 s18, s8, s18
	s_addc_u32 s19, s9, s19
	s_mulk_i32 s19, 0x3000
	s_mul_hi_u32 s21, s18, 0x3000
	s_add_i32 s21, s21, s19
	s_mulk_i32 s18, 0x3000
	s_add_u32 s18, s76, s18
	s_addc_u32 s19, s77, s21
	s_add_u32 s18, s18, 0x2000
	s_addc_u32 s19, s19, 0
	s_add_u32 s18, s18, s14
	s_addc_u32 s19, s19, 0
	v_lshrrev_b32_e32 v92, 4, v196
	v_and_b32_e32 v93, 15, v196
	v_mul_lo_u32 v94, v92, s52
	v_lshl_add_u32 v94, v93, 4, v94
	v_lshlrev_b32_e32 v93, 5, v93
	global_load_dwordx4 v[84:87], v93, s[18:19]
	global_load_dwordx4 v[88:91], v93, s[18:19] offset:16
	ds_read_b128 v[4:7], v94 offset:0
	s_waitcnt vmcnt(0) lgkmcnt(0)
	v_lshlrev_b32_e32 v8, 16, v4
	v_and_b32_e32 v9, 0xffff0000, v4
	v_lshlrev_b32_e32 v10, 16, v5
	v_and_b32_e32 v11, 0xffff0000, v5
	v_lshlrev_b32_e32 v12, 16, v6
	v_and_b32_e32 v13, 0xffff0000, v6
	v_lshlrev_b32_e32 v14, 16, v7
	v_and_b32_e32 v15, 0xffff0000, v7
	v_fmac_f32_e32 v162, v84, v8
	v_fmac_f32_e32 v163, v85, v9
	v_fmac_f32_e32 v164, v86, v10
	v_fmac_f32_e32 v165, v87, v11
	v_fmac_f32_e32 v166, v88, v12
	v_fmac_f32_e32 v167, v89, v13
	v_fmac_f32_e32 v168, v90, v14
	v_fmac_f32_e32 v169, v91, v15
	global_store_dwordx4 v242, v[162:165], s[26:27]
	global_store_dwordx4 v242, v[166:169], s[26:27] offset:16
	s_add_u32 s26, s26, 0x10000
	s_addc_u32 s27, s27, 0
	ds_read_b128 v[4:7], v94 offset:4352
	s_waitcnt lgkmcnt(0)
	v_lshlrev_b32_e32 v8, 16, v4
	v_and_b32_e32 v9, 0xffff0000, v4
	v_lshlrev_b32_e32 v10, 16, v5
	v_and_b32_e32 v11, 0xffff0000, v5
	v_lshlrev_b32_e32 v12, 16, v6
	v_and_b32_e32 v13, 0xffff0000, v6
	v_lshlrev_b32_e32 v14, 16, v7
	v_and_b32_e32 v15, 0xffff0000, v7
	v_fmac_f32_e32 v170, v84, v8
	v_fmac_f32_e32 v171, v85, v9
	v_fmac_f32_e32 v172, v86, v10
	v_fmac_f32_e32 v173, v87, v11
	v_fmac_f32_e32 v174, v88, v12
	v_fmac_f32_e32 v175, v89, v13
	v_fmac_f32_e32 v176, v90, v14
	v_fmac_f32_e32 v177, v91, v15
	global_store_dwordx4 v242, v[170:173], s[26:27]
	global_store_dwordx4 v242, v[174:177], s[26:27] offset:16
	s_add_u32 s26, s26, 0x10000
	s_addc_u32 s27, s27, 0
	ds_read_b128 v[4:7], v94 offset:8704
	s_waitcnt lgkmcnt(0)
	v_lshlrev_b32_e32 v8, 16, v4
	v_and_b32_e32 v9, 0xffff0000, v4
	v_lshlrev_b32_e32 v10, 16, v5
	v_and_b32_e32 v11, 0xffff0000, v5
	v_lshlrev_b32_e32 v12, 16, v6
	v_and_b32_e32 v13, 0xffff0000, v6
	v_lshlrev_b32_e32 v14, 16, v7
	v_and_b32_e32 v15, 0xffff0000, v7
	v_fmac_f32_e32 v178, v84, v8
	v_fmac_f32_e32 v179, v85, v9
	v_fmac_f32_e32 v180, v86, v10
	v_fmac_f32_e32 v181, v87, v11
	v_fmac_f32_e32 v182, v88, v12
	v_fmac_f32_e32 v183, v89, v13
	v_fmac_f32_e32 v184, v90, v14
	v_fmac_f32_e32 v185, v91, v15
	global_store_dwordx4 v242, v[178:181], s[26:27]
	global_store_dwordx4 v242, v[182:185], s[26:27] offset:16
	s_add_u32 s26, s26, 0x10000
	s_addc_u32 s27, s27, 0
	ds_read_b128 v[4:7], v94 offset:13056
	s_waitcnt lgkmcnt(0)
	v_lshlrev_b32_e32 v8, 16, v4
	v_and_b32_e32 v9, 0xffff0000, v4
	v_lshlrev_b32_e32 v10, 16, v5
	v_and_b32_e32 v11, 0xffff0000, v5
	v_lshlrev_b32_e32 v12, 16, v6
	v_and_b32_e32 v13, 0xffff0000, v6
	v_lshlrev_b32_e32 v14, 16, v7
	v_and_b32_e32 v15, 0xffff0000, v7
	v_fmac_f32_e32 v186, v84, v8
	v_fmac_f32_e32 v187, v85, v9
	v_fmac_f32_e32 v188, v86, v10
	v_fmac_f32_e32 v189, v87, v11
	v_fmac_f32_e32 v190, v88, v12
	v_fmac_f32_e32 v191, v89, v13
	v_fmac_f32_e32 v192, v90, v14
	v_fmac_f32_e32 v193, v91, v15
	global_store_dwordx4 v242, v[186:189], s[26:27]
	global_store_dwordx4 v242, v[190:193], s[26:27] offset:16
	s_add_u32 s26, s26, 0x10000
	s_addc_u32 s27, s27, 0
	ds_read_b128 v[4:7], v94 offset:17408
	s_waitcnt lgkmcnt(0)
	v_lshlrev_b32_e32 v8, 16, v4
	v_and_b32_e32 v9, 0xffff0000, v4
	v_lshlrev_b32_e32 v10, 16, v5
	v_and_b32_e32 v11, 0xffff0000, v5
	v_lshlrev_b32_e32 v12, 16, v6
	v_and_b32_e32 v13, 0xffff0000, v6
	v_lshlrev_b32_e32 v14, 16, v7
	v_and_b32_e32 v15, 0xffff0000, v7
	v_fmac_f32_e32 v210, v84, v8
	v_fmac_f32_e32 v211, v85, v9
	v_fmac_f32_e32 v212, v86, v10
	v_fmac_f32_e32 v213, v87, v11
	v_fmac_f32_e32 v214, v88, v12
	v_fmac_f32_e32 v215, v89, v13
	v_fmac_f32_e32 v216, v90, v14
	v_fmac_f32_e32 v217, v91, v15
	global_store_dwordx4 v242, v[210:213], s[26:27]
	global_store_dwordx4 v242, v[214:217], s[26:27] offset:16
	s_add_u32 s26, s26, 0x10000
	s_addc_u32 s27, s27, 0
	ds_read_b128 v[4:7], v94 offset:21760
	s_waitcnt lgkmcnt(0)
	v_lshlrev_b32_e32 v8, 16, v4
	v_and_b32_e32 v9, 0xffff0000, v4
	v_lshlrev_b32_e32 v10, 16, v5
	v_and_b32_e32 v11, 0xffff0000, v5
	v_lshlrev_b32_e32 v12, 16, v6
	v_and_b32_e32 v13, 0xffff0000, v6
	v_lshlrev_b32_e32 v14, 16, v7
	v_and_b32_e32 v15, 0xffff0000, v7
	v_fmac_f32_e32 v218, v84, v8
	v_fmac_f32_e32 v219, v85, v9
	v_fmac_f32_e32 v220, v86, v10
	v_fmac_f32_e32 v221, v87, v11
	v_fmac_f32_e32 v222, v88, v12
	v_fmac_f32_e32 v223, v89, v13
	v_fmac_f32_e32 v224, v90, v14
	v_fmac_f32_e32 v225, v91, v15
	global_store_dwordx4 v242, v[218:221], s[26:27]
	global_store_dwordx4 v242, v[222:225], s[26:27] offset:16
	s_add_u32 s26, s26, 0x10000
	s_addc_u32 s27, s27, 0
	ds_read_b128 v[4:7], v94 offset:26112
	s_waitcnt lgkmcnt(0)
	v_lshlrev_b32_e32 v8, 16, v4
	v_and_b32_e32 v9, 0xffff0000, v4
	v_lshlrev_b32_e32 v10, 16, v5
	v_and_b32_e32 v11, 0xffff0000, v5
	v_lshlrev_b32_e32 v12, 16, v6
	v_and_b32_e32 v13, 0xffff0000, v6
	v_lshlrev_b32_e32 v14, 16, v7
	v_and_b32_e32 v15, 0xffff0000, v7
	v_fmac_f32_e32 v226, v84, v8
	v_fmac_f32_e32 v227, v85, v9
	v_fmac_f32_e32 v228, v86, v10
	v_fmac_f32_e32 v229, v87, v11
	v_fmac_f32_e32 v230, v88, v12
	v_fmac_f32_e32 v231, v89, v13
	v_fmac_f32_e32 v232, v90, v14
	v_fmac_f32_e32 v233, v91, v15
	global_store_dwordx4 v242, v[226:229], s[26:27]
	global_store_dwordx4 v242, v[230:233], s[26:27] offset:16
	s_add_u32 s26, s26, 0x10000
	s_addc_u32 s27, s27, 0
	ds_read_b128 v[4:7], v94 offset:30464
	s_waitcnt lgkmcnt(0)
	v_lshlrev_b32_e32 v8, 16, v4
	v_and_b32_e32 v9, 0xffff0000, v4
	v_lshlrev_b32_e32 v10, 16, v5
	v_and_b32_e32 v11, 0xffff0000, v5
	v_lshlrev_b32_e32 v12, 16, v6
	v_and_b32_e32 v13, 0xffff0000, v6
	v_lshlrev_b32_e32 v14, 16, v7
	v_and_b32_e32 v15, 0xffff0000, v7
	v_fmac_f32_e32 v234, v84, v8
	v_fmac_f32_e32 v235, v85, v9
	v_fmac_f32_e32 v236, v86, v10
	v_fmac_f32_e32 v237, v87, v11
	v_fmac_f32_e32 v238, v88, v12
	v_fmac_f32_e32 v239, v89, v13
	v_fmac_f32_e32 v240, v90, v14
	v_fmac_f32_e32 v241, v91, v15
	global_store_dwordx4 v242, v[234:237], s[26:27]
	global_store_dwordx4 v242, v[238:241], s[26:27] offset:16
	s_branch .LBB0_1081
